# phase0 hand rewrite + attention prefetch + async dequeue + removed vmcnt(0) drains in GEMM K-loops
# speedup vs baseline: 1.0589x; 1.0334x over previous
.LBB0_236:
	ds_read_b128 v[144:147], v160
	ds_read_b128 v[148:151], v161
	ds_read_b128 v[178:181], v163
	ds_read_b128 v[182:185], v164
	s_add_i32 s14, s2, 2
	s_add_u32 s8, s6, 0x80
	s_addc_u32 s3, s7, 0
	s_cmp_eq_u32 s56, s2
	s_cselect_b32 s2, s62, s8
	s_cselect_b32 s3, s63, s3
	s_cselect_b32 s9, s1, s11
	s_cselect_b32 s8, s0, s10
	s_mov_b32 m0, s61
	v_lshl_add_u64 v[152:153], s[6:7], 0, v[136:137]
	ds_read_b128 v[186:189], v158
	ds_read_b128 v[190:193], v158 offset:1024
	ds_read_b128 v[194:197], v158 offset:2048
	ds_read_b128 v[198:201], v158 offset:3072
	ds_read_b128 v[202:205], v158 offset:4096
	ds_read_b128 v[206:209], v158 offset:5120
	ds_read_b128 v[210:213], v158 offset:6144
	ds_read_b128 v[214:217], v158 offset:7168
	global_load_lds_dwordx4 v[152:153], off
	v_lshl_add_u64 v[152:153], s[6:7], 0, v[138:139]
	s_mov_b32 m0, s64
	s_nop 0
	global_load_lds_dwordx4 v[152:153], off
	s_waitcnt lgkmcnt(8)
	s_barrier
	s_waitcnt lgkmcnt(0)
	s_setprio 1
	s_waitcnt lgkmcnt(0)
	v_mfma_f32_16x16x32_bf16 v[126:129], v[144:147], v[186:189], v[126:129]
	v_mfma_f32_16x16x32_bf16 v[122:125], v[178:181], v[186:189], v[122:125]
	v_mfma_f32_16x16x32_bf16 v[110:113], v[144:147], v[194:197], v[110:113]
	v_mfma_f32_16x16x32_bf16 v[106:109], v[178:181], v[194:197], v[106:109]
	v_mfma_f32_16x16x32_bf16 v[94:97], v[144:147], v[202:205], v[94:97]
	v_mfma_f32_16x16x32_bf16 v[90:93], v[178:181], v[202:205], v[90:93]
	v_mfma_f32_16x16x32_bf16 v[78:81], v[144:147], v[210:213], v[78:81]
	v_mfma_f32_16x16x32_bf16 v[74:77], v[178:181], v[210:213], v[74:77]
	v_mfma_f32_16x16x32_bf16 v[126:129], v[148:151], v[190:193], v[126:129]
	v_mfma_f32_16x16x32_bf16 v[122:125], v[182:185], v[190:193], v[122:125]
	v_mfma_f32_16x16x32_bf16 v[110:113], v[148:151], v[198:201], v[110:113]
	v_mfma_f32_16x16x32_bf16 v[106:109], v[182:185], v[198:201], v[106:109]
	v_mfma_f32_16x16x32_bf16 v[94:97], v[148:151], v[206:209], v[94:97]
	v_mfma_f32_16x16x32_bf16 v[90:93], v[182:185], v[206:209], v[90:93]
	v_mfma_f32_16x16x32_bf16 v[78:81], v[148:151], v[214:217], v[78:81]
	v_mfma_f32_16x16x32_bf16 v[74:77], v[182:185], v[214:217], v[74:77]
	s_setprio 0
	s_barrier
	s_mov_b32 m0, s30
	v_lshl_add_u64 v[152:153], s[8:9], 0, v[130:131]
	ds_read_b128 v[218:221], v165
	ds_read_b128 v[222:225], v166
	ds_read_b128 v[226:229], v167
	ds_read_b128 v[230:233], v168
	global_load_lds_dwordx4 v[152:153], off
	v_lshl_add_u64 v[234:235], s[8:9], 0, v[132:133]
	s_mov_b32 m0, s31
	s_nop 0
	global_load_lds_dwordx4 v[234:235], off
	s_barrier
	s_waitcnt lgkmcnt(0)
	s_setprio 1
	s_waitcnt lgkmcnt(0)
	v_mfma_f32_16x16x32_bf16 v[118:121], v[218:221], v[186:189], v[118:121]
	v_mfma_f32_16x16x32_bf16 v[114:117], v[226:229], v[186:189], v[114:117]
	v_mfma_f32_16x16x32_bf16 v[102:105], v[218:221], v[194:197], v[102:105]
	v_mfma_f32_16x16x32_bf16 v[98:101], v[226:229], v[194:197], v[98:101]
	v_mfma_f32_16x16x32_bf16 v[86:89], v[218:221], v[202:205], v[86:89]
	v_mfma_f32_16x16x32_bf16 v[82:85], v[226:229], v[202:205], v[82:85]
	v_mfma_f32_16x16x32_bf16 v[70:73], v[218:221], v[210:213], v[70:73]
	v_mfma_f32_16x16x32_bf16 v[66:69], v[226:229], v[210:213], v[66:69]
	v_mfma_f32_16x16x32_bf16 v[118:121], v[222:225], v[190:193], v[118:121]
	v_mfma_f32_16x16x32_bf16 v[114:117], v[230:233], v[190:193], v[114:117]
	v_mfma_f32_16x16x32_bf16 v[102:105], v[222:225], v[198:201], v[102:105]
	v_mfma_f32_16x16x32_bf16 v[98:101], v[230:233], v[198:201], v[98:101]
	v_mfma_f32_16x16x32_bf16 v[86:89], v[222:225], v[206:209], v[86:89]
	v_mfma_f32_16x16x32_bf16 v[82:85], v[230:233], v[206:209], v[82:85]
	v_mfma_f32_16x16x32_bf16 v[70:73], v[222:225], v[214:217], v[70:73]
	v_mfma_f32_16x16x32_bf16 v[66:69], v[230:233], v[214:217], v[66:69]
	s_setprio 0
	s_mov_b32 m0, s29
	v_lshl_add_u64 v[236:237], s[2:3], 0, v[130:131]
	s_barrier
	ds_read_b128 v[186:189], v158 offset:16384
	ds_read_b128 v[190:193], v158 offset:17408
	ds_read_b128 v[194:197], v158 offset:18432
	ds_read_b128 v[198:201], v158 offset:19456
	ds_read_b128 v[202:205], v158 offset:20480
	ds_read_b128 v[206:209], v158 offset:21504
	ds_read_b128 v[210:213], v158 offset:22528
	ds_read_b128 v[214:217], v158 offset:23552
	global_load_lds_dwordx4 v[236:237], off
	v_lshl_add_u64 v[238:239], s[2:3], 0, v[132:133]
	s_mov_b32 m0, s33
	s_nop 0
	global_load_lds_dwordx4 v[238:239], off
	s_barrier
	s_waitcnt lgkmcnt(0)
	s_setprio 1
	s_waitcnt lgkmcnt(0)
	v_mfma_f32_16x16x32_bf16 v[62:65], v[144:147], v[186:189], v[62:65]
	v_mfma_f32_16x16x32_bf16 v[58:61], v[178:181], v[186:189], v[58:61]
	v_mfma_f32_16x16x32_bf16 v[46:49], v[144:147], v[194:197], v[46:49]
	v_mfma_f32_16x16x32_bf16 v[42:45], v[178:181], v[194:197], v[42:45]
	v_mfma_f32_16x16x32_bf16 v[30:33], v[144:147], v[202:205], v[30:33]
	v_mfma_f32_16x16x32_bf16 v[26:29], v[178:181], v[202:205], v[26:29]
	v_mfma_f32_16x16x32_bf16 v[14:17], v[144:147], v[210:213], v[14:17]
	v_mfma_f32_16x16x32_bf16 v[10:13], v[178:181], v[210:213], v[10:13]
	v_mfma_f32_16x16x32_bf16 v[62:65], v[148:151], v[190:193], v[62:65]
	v_mfma_f32_16x16x32_bf16 v[58:61], v[182:185], v[190:193], v[58:61]
	v_mfma_f32_16x16x32_bf16 v[46:49], v[148:151], v[198:201], v[46:49]
	v_mfma_f32_16x16x32_bf16 v[42:45], v[182:185], v[198:201], v[42:45]
	v_mfma_f32_16x16x32_bf16 v[30:33], v[148:151], v[206:209], v[30:33]
	v_mfma_f32_16x16x32_bf16 v[26:29], v[182:185], v[206:209], v[26:29]
	v_mfma_f32_16x16x32_bf16 v[14:17], v[148:151], v[214:217], v[14:17]
	v_mfma_f32_16x16x32_bf16 v[10:13], v[182:185], v[214:217], v[10:13]
	s_setprio 0
	s_barrier
	s_add_u32 s8, s8, s18
	s_addc_u32 s9, s9, s19
	s_mov_b32 m0, s34
	v_lshl_add_u64 v[240:241], s[8:9], 0, v[130:131]
	global_load_lds_dwordx4 v[240:241], off
	v_lshl_add_u64 v[242:243], s[8:9], 0, v[132:133]
	s_mov_b32 m0, s35
	s_nop 0
	global_load_lds_dwordx4 v[242:243], off
	s_waitcnt vmcnt(6)
	s_barrier
	s_setprio 1
	v_mfma_f32_16x16x32_bf16 v[54:57], v[218:221], v[186:189], v[54:57]
	v_mfma_f32_16x16x32_bf16 v[50:53], v[226:229], v[186:189], v[50:53]
	v_mfma_f32_16x16x32_bf16 v[38:41], v[218:221], v[194:197], v[38:41]
	v_mfma_f32_16x16x32_bf16 v[34:37], v[226:229], v[194:197], v[34:37]
	v_mfma_f32_16x16x32_bf16 v[22:25], v[218:221], v[202:205], v[22:25]
	v_mfma_f32_16x16x32_bf16 v[18:21], v[226:229], v[202:205], v[18:21]
	v_mfma_f32_16x16x32_bf16 v[6:9], v[218:221], v[210:213], v[6:9]
	v_mfma_f32_16x16x32_bf16 v[2:5], v[226:229], v[210:213], v[2:5]
	v_mfma_f32_16x16x32_bf16 v[54:57], v[222:225], v[190:193], v[54:57]
	v_mfma_f32_16x16x32_bf16 v[50:53], v[230:233], v[190:193], v[50:53]
	v_mfma_f32_16x16x32_bf16 v[38:41], v[222:225], v[198:201], v[38:41]
	v_mfma_f32_16x16x32_bf16 v[34:37], v[230:233], v[198:201], v[34:37]
	v_mfma_f32_16x16x32_bf16 v[22:25], v[222:225], v[206:209], v[22:25]
	v_mfma_f32_16x16x32_bf16 v[18:21], v[230:233], v[206:209], v[18:21]
	v_mfma_f32_16x16x32_bf16 v[6:9], v[222:225], v[214:217], v[6:9]
	v_mfma_f32_16x16x32_bf16 v[2:5], v[230:233], v[214:217], v[2:5]
	s_setprio 0
	s_barrier
	ds_read_b128 v[144:147], v169
	ds_read_b128 v[148:151], v170
	ds_read_b128 v[178:181], v171
	ds_read_b128 v[182:185], v172
	s_add_u32 s2, s2, s18
	s_addc_u32 s3, s3, s19
	s_mov_b32 m0, s38
	v_lshl_add_u64 v[218:219], s[2:3], 0, v[130:131]
	ds_read_b128 v[186:189], v158 offset:32768
	ds_read_b128 v[190:193], v158 offset:33792
	ds_read_b128 v[194:197], v158 offset:34816
	ds_read_b128 v[198:201], v158 offset:35840
	ds_read_b128 v[202:205], v158 offset:36864
	ds_read_b128 v[206:209], v158 offset:37888
	ds_read_b128 v[210:213], v158 offset:38912
	ds_read_b128 v[214:217], v158 offset:39936
	global_load_lds_dwordx4 v[218:219], off
	v_lshl_add_u64 v[218:219], s[2:3], 0, v[132:133]
	s_mov_b32 m0, s39
	s_nop 0
	global_load_lds_dwordx4 v[218:219], off
	s_waitcnt lgkmcnt(8)
	s_barrier
	s_waitcnt lgkmcnt(0)
	s_setprio 1
	s_waitcnt lgkmcnt(0)
	v_mfma_f32_16x16x32_bf16 v[126:129], v[144:147], v[186:189], v[126:129]
	v_mfma_f32_16x16x32_bf16 v[122:125], v[178:181], v[186:189], v[122:125]
	v_mfma_f32_16x16x32_bf16 v[110:113], v[144:147], v[194:197], v[110:113]
	v_mfma_f32_16x16x32_bf16 v[106:109], v[178:181], v[194:197], v[106:109]
	v_mfma_f32_16x16x32_bf16 v[94:97], v[144:147], v[202:205], v[94:97]
	v_mfma_f32_16x16x32_bf16 v[90:93], v[178:181], v[202:205], v[90:93]
	v_mfma_f32_16x16x32_bf16 v[78:81], v[144:147], v[210:213], v[78:81]
	v_mfma_f32_16x16x32_bf16 v[74:77], v[178:181], v[210:213], v[74:77]
	v_mfma_f32_16x16x32_bf16 v[126:129], v[148:151], v[190:193], v[126:129]
	v_mfma_f32_16x16x32_bf16 v[122:125], v[182:185], v[190:193], v[122:125]
	v_mfma_f32_16x16x32_bf16 v[110:113], v[148:151], v[198:201], v[110:113]
	v_mfma_f32_16x16x32_bf16 v[106:109], v[182:185], v[198:201], v[106:109]
	v_mfma_f32_16x16x32_bf16 v[94:97], v[148:151], v[206:209], v[94:97]
	v_mfma_f32_16x16x32_bf16 v[90:93], v[182:185], v[206:209], v[90:93]
	v_mfma_f32_16x16x32_bf16 v[78:81], v[148:151], v[214:217], v[78:81]
	v_mfma_f32_16x16x32_bf16 v[74:77], v[182:185], v[214:217], v[74:77]
	s_setprio 0
	s_barrier
	s_mov_b32 m0, s41
	v_lshl_add_u64 v[152:153], v[152:153], 0, s[22:23]
	ds_read_b128 v[218:221], v173
	ds_read_b128 v[222:225], v174
	ds_read_b128 v[226:229], v175
	ds_read_b128 v[230:233], v176
	global_load_lds_dwordx4 v[152:153], off
	v_lshl_add_u64 v[152:153], v[234:235], 0, s[22:23]
	s_mov_b32 m0, s42
	s_nop 0
	global_load_lds_dwordx4 v[152:153], off
	s_barrier
	s_waitcnt lgkmcnt(0)
	s_setprio 1
	s_waitcnt lgkmcnt(0)
	v_mfma_f32_16x16x32_bf16 v[118:121], v[218:221], v[186:189], v[118:121]
	v_mfma_f32_16x16x32_bf16 v[114:117], v[226:229], v[186:189], v[114:117]
	v_mfma_f32_16x16x32_bf16 v[102:105], v[218:221], v[194:197], v[102:105]
	v_mfma_f32_16x16x32_bf16 v[98:101], v[226:229], v[194:197], v[98:101]
	v_mfma_f32_16x16x32_bf16 v[86:89], v[218:221], v[202:205], v[86:89]
	v_mfma_f32_16x16x32_bf16 v[82:85], v[226:229], v[202:205], v[82:85]
	v_mfma_f32_16x16x32_bf16 v[70:73], v[218:221], v[210:213], v[70:73]
	v_mfma_f32_16x16x32_bf16 v[66:69], v[226:229], v[210:213], v[66:69]
	v_mfma_f32_16x16x32_bf16 v[118:121], v[222:225], v[190:193], v[118:121]
	v_mfma_f32_16x16x32_bf16 v[114:117], v[230:233], v[190:193], v[114:117]
	v_mfma_f32_16x16x32_bf16 v[102:105], v[222:225], v[198:201], v[102:105]
	v_mfma_f32_16x16x32_bf16 v[98:101], v[230:233], v[198:201], v[98:101]
	v_mfma_f32_16x16x32_bf16 v[86:89], v[222:225], v[206:209], v[86:89]
	v_mfma_f32_16x16x32_bf16 v[82:85], v[230:233], v[206:209], v[82:85]
	v_mfma_f32_16x16x32_bf16 v[70:73], v[222:225], v[214:217], v[70:73]
	v_mfma_f32_16x16x32_bf16 v[66:69], v[230:233], v[214:217], v[66:69]
	s_setprio 0
	s_mov_b32 m0, s43
	v_lshl_add_u64 v[152:153], v[236:237], 0, s[22:23]
	s_barrier
	ds_read_b128 v[186:189], v158 offset:49152
	ds_read_b128 v[190:193], v158 offset:50176
	ds_read_b128 v[194:197], v158 offset:51200
	ds_read_b128 v[198:201], v158 offset:52224
	ds_read_b128 v[202:205], v158 offset:53248
	ds_read_b128 v[206:209], v158 offset:54272
	ds_read_b128 v[210:213], v158 offset:55296
	ds_read_b128 v[214:217], v158 offset:56320
	global_load_lds_dwordx4 v[152:153], off
	v_lshl_add_u64 v[152:153], v[238:239], 0, s[22:23]
	s_mov_b32 m0, s48
	s_nop 0
	global_load_lds_dwordx4 v[152:153], off
	s_barrier
	s_waitcnt lgkmcnt(0)
	s_setprio 1
	s_waitcnt lgkmcnt(0)
	v_mfma_f32_16x16x32_bf16 v[62:65], v[144:147], v[186:189], v[62:65]
	v_mfma_f32_16x16x32_bf16 v[58:61], v[178:181], v[186:189], v[58:61]
	v_mfma_f32_16x16x32_bf16 v[46:49], v[144:147], v[194:197], v[46:49]
	v_mfma_f32_16x16x32_bf16 v[42:45], v[178:181], v[194:197], v[42:45]
	v_mfma_f32_16x16x32_bf16 v[30:33], v[144:147], v[202:205], v[30:33]
	v_mfma_f32_16x16x32_bf16 v[26:29], v[178:181], v[202:205], v[26:29]
	v_mfma_f32_16x16x32_bf16 v[14:17], v[144:147], v[210:213], v[14:17]
	v_mfma_f32_16x16x32_bf16 v[10:13], v[178:181], v[210:213], v[10:13]
	v_mfma_f32_16x16x32_bf16 v[62:65], v[148:151], v[190:193], v[62:65]
	v_mfma_f32_16x16x32_bf16 v[58:61], v[182:185], v[190:193], v[58:61]
	v_mfma_f32_16x16x32_bf16 v[46:49], v[148:151], v[198:201], v[46:49]
	v_mfma_f32_16x16x32_bf16 v[42:45], v[182:185], v[198:201], v[42:45]
	v_mfma_f32_16x16x32_bf16 v[30:33], v[148:151], v[206:209], v[30:33]
	v_mfma_f32_16x16x32_bf16 v[26:29], v[182:185], v[206:209], v[26:29]
	v_mfma_f32_16x16x32_bf16 v[14:17], v[148:151], v[214:217], v[14:17]
	v_mfma_f32_16x16x32_bf16 v[10:13], v[182:185], v[214:217], v[10:13]
	s_setprio 0
	s_barrier
	s_mov_b32 m0, s49
	v_lshl_add_u64 v[144:145], v[240:241], 0, s[22:23]
	global_load_lds_dwordx4 v[144:145], off
	v_lshl_add_u64 v[144:145], v[242:243], 0, s[22:23]
	s_mov_b32 m0, s50
	s_nop 0
	global_load_lds_dwordx4 v[144:145], off
	s_waitcnt vmcnt(6)
	s_barrier
	s_setprio 1
	v_mfma_f32_16x16x32_bf16 v[54:57], v[218:221], v[186:189], v[54:57]
	v_mfma_f32_16x16x32_bf16 v[50:53], v[226:229], v[186:189], v[50:53]
	v_mfma_f32_16x16x32_bf16 v[38:41], v[218:221], v[194:197], v[38:41]
	v_mfma_f32_16x16x32_bf16 v[34:37], v[226:229], v[194:197], v[34:37]
	v_mfma_f32_16x16x32_bf16 v[22:25], v[218:221], v[202:205], v[22:25]
	v_mfma_f32_16x16x32_bf16 v[18:21], v[226:229], v[202:205], v[18:21]
	v_mfma_f32_16x16x32_bf16 v[6:9], v[218:221], v[210:213], v[6:9]
	v_mfma_f32_16x16x32_bf16 v[2:5], v[226:229], v[210:213], v[2:5]
	v_mfma_f32_16x16x32_bf16 v[54:57], v[222:225], v[190:193], v[54:57]
	v_mfma_f32_16x16x32_bf16 v[50:53], v[230:233], v[190:193], v[50:53]
	v_mfma_f32_16x16x32_bf16 v[38:41], v[222:225], v[198:201], v[38:41]
	v_mfma_f32_16x16x32_bf16 v[34:37], v[230:233], v[198:201], v[34:37]
	v_mfma_f32_16x16x32_bf16 v[22:25], v[222:225], v[206:209], v[22:25]
	v_mfma_f32_16x16x32_bf16 v[18:21], v[230:233], v[206:209], v[18:21]
	v_mfma_f32_16x16x32_bf16 v[6:9], v[222:225], v[214:217], v[6:9]
	v_mfma_f32_16x16x32_bf16 v[2:5], v[230:233], v[214:217], v[2:5]
	s_setprio 0
	s_add_u32 s6, s6, 0x100
	s_addc_u32 s7, s7, 0
	s_add_u32 s10, s10, 0x100
	s_addc_u32 s11, s11, 0
	s_cmp_ge_i32 s14, s51
	s_mov_b32 s2, s14
	s_barrier
	s_cbranch_scc0 .LBB0_236

.LBB0_670:
	s_mov_b32 s5, s0
	s_add_i32 s0, s0, s92
	s_and_b32 s0, s0, 7
	s_lshl_b32 s1, s0, 8
	v_readlane_b32 s2, v251, 50
	s_add_u32 s2, s2, s1
	v_readlane_b32 s1, v251, 51
	s_addc_u32 s3, s1, 0
	v_writelane_b32 v250, s2, 10
	s_mul_i32 s1, s0, 0x208
	s_addk_i32 s1, 0x1040
	v_writelane_b32 v250, s3, 11
	v_writelane_b32 v250, s1, 12
	s_lshl_b32 s1, s0, 9
	s_add_i32 s1, s1, -8
	s_lshl_b32 s0, s0, 3
	v_writelane_b32 v250, s1, 13
	s_bitset1_b32 s0, 12
	v_writelane_b32 v250, s0, 14
	s_cmp_eq_u32 s5, 0
	s_cbranch_scc1 .Ldq_issue
	s_cmp_eq_u32 s5, 1
	s_cbranch_scc0 .Ldq_have_snap
	v_mbcnt_lo_u32_b32 v239, -1, 0
	v_mbcnt_hi_u32_b32 v239, -1, v239
	v_lshlrev_b32_e32 v239, 8, v239
	v_readlane_b32 s0, v251, 50
	v_readlane_b32 s1, v251, 51
	s_mov_b64 s[10:11], exec
	s_mov_b64 exec, 0xff
	s_nop 4
	global_load_dword v239, v239, s[0:1] sc1
	s_mov_b64 exec, s[10:11]
	s_waitcnt vmcnt(0)
.Ldq_have_snap:
	s_add_i32 s0, s5, s92
	s_and_b32 s0, s0, 7
	s_nop 0
	v_readlane_b32 s1, v239, s0
	s_cmpk_gt_u32 s1, 0x40f
	s_cbranch_scc1 .LBB0_669
.Ldq_issue:
	s_mov_b64 s[10:11], exec
	s_mov_b64 exec, 1
	v_mov_b32_e32 v238, 1
	global_atomic_add v238, v91, v238, s[2:3] sc0
	s_mov_b64 exec, s[10:11]
	s_branch .LBB0_674

.LBB0_674:
	s_waitcnt vmcnt(0)
	v_readfirstlane_b32 s3, v238
	s_cmpk_gt_u32 s3, 0x40f
	s_mov_b64 s[0:1], -1
	s_cbranch_scc1 .LBB0_673
	v_readlane_b32 s10, v250, 10
	v_readlane_b32 s11, v250, 11
	s_mov_b64 vcc, exec
	s_mov_b64 exec, 1
	v_mov_b32_e32 v238, 1
	s_nop 2
	global_atomic_add v238, v91, v238, s[10:11] sc0
	s_mov_b64 exec, vcc
	s_mov_b64 s[0:1], -1
	s_lshr_b32 s2, s3, 1
	s_bitcmp0_b32 s3, 0
	s_cbranch_scc1 .LBB0_681
	v_readlane_b32 s0, v250, 12
	s_add_i32 s18, s0, s2
	s_mov_b64 s[0:1], 0

.LBB0_835:
	v_lshl_add_u64 v[18:19], s[0:1], 0, v[94:95]
	v_mov_b64_e32 v[20:21], s[94:95]
	v_mad_u64_u32 v[22:23], s[2:3], v18, s14, v[20:21]
	v_mov_b32_e32 v18, v23
	v_mad_u64_u32 v[18:19], s[2:3], v19, s14, v[18:19]
	v_mov_b32_e32 v23, v18
	s_lshl_b32 s2, s10, 1
	s_mov_b32 s3, s9
	v_lshl_add_u64 v[18:19], v[22:23], 0, s[2:3]
	v_lshlrev_b32_e32 v90, 1, v92
	v_lshl_add_u64 v[18:19], v[18:19], 0, v[90:91]
	global_load_dwordx4 v[34:37], v[18:19], off offset:1024
	global_load_dwordx4 v[38:41], v[18:19], off offset:1088
	v_lshl_add_u64 v[22:23], v[18:19], 0, s[40:41]
	v_add_co_u32_e32 v18, vcc, s15, v18
	v_lshlrev_b32_e32 v90, 1, v118
	s_nop 0
	v_addc_co_u32_e32 v19, vcc, 0, v19, vcc
	global_load_dwordx4 v[42:45], v[18:19], off offset:1024
	global_load_dwordx4 v[46:49], v[22:23], off offset:64
	v_lshl_add_u64 v[18:19], s[0:1], 0, v[116:117]
	v_mad_u64_u32 v[20:21], s[0:1], v18, s14, v[20:21]
	v_mov_b32_e32 v18, v21
	v_mad_u64_u32 v[18:19], s[0:1], v19, s14, v[18:19]
	v_mov_b32_e32 v21, v18
	v_lshl_add_u64 v[18:19], v[20:21], 0, s[2:3]
	v_lshl_add_u64 v[22:23], v[18:19], 0, v[90:91]
	global_load_dwordx4 v[174:177], v[22:23], off offset:2048
	global_load_dwordx4 v[178:181], v[22:23], off offset:2064
	global_load_dwordx4 v[182:185], v[22:23], off offset:2080
	global_load_dwordx4 v[186:189], v[22:23], off offset:2096
	s_waitcnt vmcnt(3)
	ds_write_b16 v145, v174
	ds_write_b16_d16_hi v145, v174 offset:72
	ds_write_b16 v145, v175 offset:144
	ds_write_b16_d16_hi v145, v175 offset:216
	ds_write_b16 v145, v176 offset:288
	ds_write_b16_d16_hi v145, v176 offset:360
	ds_write_b16 v145, v177 offset:432
	ds_write_b16_d16_hi v145, v177 offset:504
	s_waitcnt vmcnt(2)
	ds_write_b16 v145, v178 offset:576
	ds_write_b16_d16_hi v145, v178 offset:648
	ds_write_b16 v145, v179 offset:720
	ds_write_b16_d16_hi v145, v179 offset:792
	ds_write_b16 v145, v180 offset:864
	ds_write_b16_d16_hi v145, v180 offset:936
	ds_write_b16 v145, v181 offset:1008
	ds_write_b16_d16_hi v145, v181 offset:1080
	s_waitcnt vmcnt(1)
	ds_write_b16 v145, v182 offset:1152
	ds_write_b16_d16_hi v145, v182 offset:1224
	ds_write_b16 v145, v183 offset:1296
	ds_write_b16_d16_hi v145, v183 offset:1368
	ds_write_b16 v145, v184 offset:1440
	ds_write_b16_d16_hi v145, v184 offset:1512
	ds_write_b16 v145, v185 offset:1584
	ds_write_b16_d16_hi v145, v185 offset:1656
	s_waitcnt vmcnt(0)
	ds_write_b16 v145, v186 offset:1728
	ds_write_b16_d16_hi v145, v186 offset:1800
	ds_write_b16 v145, v187 offset:1872
	ds_write_b16_d16_hi v145, v187 offset:1944
	ds_write_b16 v145, v188 offset:2016
	ds_write_b16_d16_hi v145, v188 offset:2088
	ds_write_b16 v145, v189 offset:2160
	v_lshrrev_b32_e32 v1, 16, v189

.LBB0_860:
	s_or_b64 exec, exec, s[0:1]
	v_sub_f32_e32 v38, v38, v76
	v_add_f32_e32 v76, 0, v83
	v_sub_f32_e32 v39, v39, v77
	v_add_f32_e32 v77, v82, v76
	v_sub_f32_e32 v38, v38, v77
	v_exp_f32_e32 v38, v38
	v_add_f32_e32 v77, v81, v76
	v_sub_f32_e32 v39, v39, v77
	v_exp_f32_e32 v39, v39
	v_sub_f32_e32 v40, v40, v78
	v_cndmask_b32_e64 v77, 0, v38, s[72:73]
	v_add_f32_e32 v38, v79, v76
	v_sub_f32_e32 v41, v41, v80
	v_sub_f32_e32 v38, v40, v38
	v_exp_f32_e32 v79, v38
	v_sub_f32_e32 v38, v41, v76
	v_cndmask_b32_e64 v78, 0, v39, s[68:69]
	v_exp_f32_e32 v76, v38
	s_waitcnt lgkmcnt(0)
	v_pk_add_f32 v[38:39], v[48:49], v[70:71]
	v_add_f32_e32 v40, v1, v72
	v_add_f32_e32 v48, v73, v74
	v_mov_b32_e32 v49, v38
	v_mov_b32_e32 v41, v39
	v_pk_add_f32 v[70:71], v[48:49], v[40:41]
	v_sub_f32_e32 v36, v36, v42
	v_add_f32_e32 v1, 0, v71
	v_add_f32_e32 v1, v75, v1
	v_add_f32_e32 v38, v1, v43
	v_sub_f32_e32 v37, v37, v43
	v_sub_f32_e32 v36, v36, v38
	v_sub_f32_e32 v35, v35, v44
	v_add_f32_e32 v38, v1, v45
	v_sub_f32_e32 v37, v37, v1
	v_sub_f32_e32 v35, v35, v38
	v_sub_f32_e32 v34, v34, v46
	v_add_f32_e32 v1, v1, v47
	v_exp_f32_e32 v37, v37
	v_exp_f32_e32 v35, v35
	v_sub_f32_e32 v1, v34, v1
	v_cndmask_b32_e64 v38, 0, v79, s[30:31]
	v_cndmask_b32_e64 v39, 0, v76, s[34:35]
	v_exp_f32_e32 v1, v1
	v_exp_f32_e32 v36, v36
	v_cvt_pk_bf16_f32 v34, v1, v35
	v_cvt_pk_bf16_f32 v35, v36, v37
	v_cvt_pk_bf16_f32 v37, v38, v39
	v_pk_add_f32 v[38:39], v[66:67], v[68:69]
	v_cvt_pk_bf16_f32 v36, v77, v78
	s_nop 0
	v_add_f32_e32 v1, v38, v39
	v_add_f32_e32 v155, 0, v1
	v_add_f32_e32 v1, v70, v71
	v_add_f32_e32 v1, 0, v1
	v_mfma_f32_16x16x32_bf16 v[46:49], v[50:53], v[34:37], 0
	v_min_f32_e32 v50, v155, v1
	v_cmp_lt_f32_e32 vcc, s17, v50
	s_cmp_eq_u64 vcc, exec
	v_mfma_f32_16x16x32_bf16 v[42:45], v[58:61], v[34:37], 0
	s_cselect_b64 s[0:1], -1, 0
	s_cmp_eq_u32 s20, 0
	s_cselect_b64 s[2:3], -1, 0
	v_mfma_f32_16x16x32_bf16 v[38:41], v[62:65], v[34:37], 0
	s_or_b64 s[0:1], s[2:3], s[0:1]
	s_and_b64 vcc, exec, s[0:1]
	v_mfma_f32_16x16x32_bf16 v[34:37], v[54:57], v[34:37], 0
	s_cbranch_vccnz .LBB0_671
	s_lshr_b32 s27, s20, 5
	s_sub_i32 s18, s20, 32
	s_addk_i32 s20, 0xf7e0
	v_lshl_add_u64 v[138:139], v[122:123], 0, s[8:9]
	v_lshl_add_u64 v[140:141], v[124:125], 0, s[8:9]
	s_lshl_b32 s8, s10, 1
	s_ashr_i32 s0, s20, 31
	s_add_u32 s20, s78, s20
	s_addc_u32 s21, s79, s0
	s_add_i32 s0, s26, s19
	s_add_i32 s0, s0, s11
	v_lshl_add_u64 v[142:143], v[130:131], 0, s[8:9]
	v_add_u32_e32 v144, s0, v93
	s_add_i32 s11, s18, s26
	s_mov_b64 s[78:79], 0
	s_and_b64 vcc, exec, s[22:23]
	s_cbranch_vccz .Lpf_skip_pre
	v_mov_b32_e32 v216, 0xfffe8000
	v_mov_b32_e32 v217, -1
	s_add_u32 s0, s76, s18
	s_addc_u32 s1, s77, 0
	v_lshl_add_u64 v[214:215], s[0:1], 0, v[116:117]
	v_mad_u64_u32 v[206:207], s[2:3], v214, s14, v[142:143]
	v_mov_b32_e32 v214, v207
	v_mad_u64_u32 v[214:215], s[2:3], v215, s14, v[214:215]
	v_mov_b32_e32 v207, v214
	v_lshl_add_u64 v[214:215], s[0:1], 0, v[94:95]
	v_mov_b64_e32 v[208:209], s[94:95]
	v_mad_u64_u32 v[208:209], s[2:3], v214, s14, v[208:209]
	v_mov_b32_e32 v214, v209
	v_mad_u64_u32 v[214:215], s[2:3], v215, s14, v[214:215]
	v_mov_b32_e32 v209, v214
	v_lshlrev_b32_e32 v90, 1, v92
	v_lshl_add_u64 v[208:209], v[208:209], 0, s[8:9]
	v_lshl_add_u64 v[208:209], v[208:209], 0, v[90:91]
	v_lshl_add_u64 v[212:213], v[208:209], 0, s[40:41]
	v_add_co_u32_e32 v210, vcc, s15, v208
	s_nop 1
	v_addc_co_u32_e32 v211, vcc, 0, v209, vcc
	global_load_dwordx4 v[174:177], v[206:207], off offset:2048
	global_load_dwordx4 v[178:181], v[206:207], off offset:2064
	global_load_dwordx4 v[182:185], v[206:207], off offset:2080
	global_load_dwordx4 v[186:189], v[206:207], off offset:2096
	global_load_dwordx4 v[190:193], v[208:209], off offset:1024
	global_load_dwordx4 v[194:197], v[208:209], off offset:1088
	global_load_dwordx4 v[198:201], v[210:211], off offset:1024
	global_load_dwordx4 v[202:205], v[212:213], off offset:64
.Lpf_skip_pre:
.LBB0_862:
	s_add_i32 s19, s27, -1
	s_cmp_lt_u32 s19, 64
	s_cselect_b64 s[2:3], -1, 0
	s_xor_b64 s[28:29], s[22:23], -1
	s_and_b64 s[2:3], s[28:29], s[2:3]
	s_mov_b64 s[0:1], -1
	s_and_b64 vcc, exec, s[2:3]
	s_cbranch_vccz .LBB0_864
	s_add_i32 s0, s11, s78
	s_ashr_i32 s1, s0, 31
	s_lshl_b64 s[0:1], s[0:1], 11
	v_lshl_add_u64 v[68:69], v[138:139], 0, s[0:1]
	v_add_u32_e32 v66, s78, v144
	v_ashrrev_i32_e32 v67, 31, v66
	v_lshlrev_b64 v[66:67], 11, v[66:67]
	v_lshl_add_u64 v[82:83], v[140:141], 0, v[66:67]
	v_lshl_add_u64 v[70:71], v[68:69], 0, s[36:37]
	global_load_dwordx4 v[174:177], v[68:69], off nt
	global_load_dwordx4 v[178:181], v[68:69], off offset:16 nt
	global_load_dwordx4 v[182:185], v[68:69], off offset:128 nt
	global_load_dwordx4 v[186:189], v[68:69], off offset:144 nt
	global_load_dwordx4 v[190:193], v[70:71], off nt
	global_load_dwordx4 v[194:197], v[70:71], off offset:16 nt
	global_load_dwordx4 v[198:201], v[70:71], off offset:128 nt
	global_load_dwordx4 v[202:205], v[70:71], off offset:144 nt
	global_load_dwordx4 v[206:209], v[82:83], off nt
	global_load_dwordx4 v[210:213], v[82:83], off offset:16 nt
	global_load_dwordx4 v[214:217], v[82:83], off offset:32 nt
	global_load_dwordx4 v[218:221], v[82:83], off offset:48 nt
	global_load_dwordx4 v[222:225], v[82:83], off offset:64 nt
	global_load_dwordx4 v[226:229], v[82:83], off offset:80 nt
	global_load_dwordx4 v[230:233], v[82:83], off offset:96 nt
	global_load_dwordx4 v[234:237], v[82:83], off offset:112 nt
	s_mov_b64 s[0:1], 0
	s_waitcnt vmcnt(14)
	v_cvt_pk_bf16_f32 v54, v174, v175
	v_cvt_pk_bf16_f32 v55, v176, v177
	v_cvt_pk_bf16_f32 v56, v178, v179
	v_cvt_pk_bf16_f32 v57, v180, v181
	s_waitcnt vmcnt(12)
	v_cvt_pk_bf16_f32 v58, v182, v183
	v_cvt_pk_bf16_f32 v59, v184, v185
	v_cvt_pk_bf16_f32 v60, v186, v187
	v_cvt_pk_bf16_f32 v61, v188, v189
	s_waitcnt vmcnt(10)
	v_cvt_pk_bf16_f32 v62, v190, v191
	v_cvt_pk_bf16_f32 v63, v192, v193
	v_cvt_pk_bf16_f32 v64, v194, v195
	v_cvt_pk_bf16_f32 v65, v196, v197
	s_waitcnt vmcnt(8)
	v_cvt_pk_bf16_f32 v50, v198, v199
	v_cvt_pk_bf16_f32 v51, v200, v201
	v_cvt_pk_bf16_f32 v52, v202, v203
	v_cvt_pk_bf16_f32 v53, v204, v205
	s_waitcnt vmcnt(7)
	v_bfe_u32 v72, v206, 16, 1
	v_add3_u32 v72, v206, v72, s33
	ds_write_b16_d16_hi v145, v72
	v_bfe_u32 v72, v207, 16, 1
	v_add3_u32 v72, v207, v72, s33
	ds_write_b16_d16_hi v145, v72 offset:72
	v_bfe_u32 v72, v208, 16, 1
	v_add3_u32 v72, v208, v72, s33
	ds_write_b16_d16_hi v145, v72 offset:144
	v_bfe_u32 v72, v209, 16, 1
	v_add3_u32 v72, v209, v72, s33
	ds_write_b16_d16_hi v145, v72 offset:216
	s_waitcnt vmcnt(6)
	v_bfe_u32 v72, v210, 16, 1
	v_add3_u32 v72, v210, v72, s33
	ds_write_b16_d16_hi v145, v72 offset:288
	v_bfe_u32 v72, v211, 16, 1
	v_add3_u32 v72, v211, v72, s33
	ds_write_b16_d16_hi v145, v72 offset:360
	v_bfe_u32 v72, v212, 16, 1
	v_add3_u32 v72, v212, v72, s33
	ds_write_b16_d16_hi v145, v72 offset:432
	v_bfe_u32 v72, v213, 16, 1
	v_add3_u32 v72, v213, v72, s33
	ds_write_b16_d16_hi v145, v72 offset:504
	s_waitcnt vmcnt(5)
	v_bfe_u32 v72, v214, 16, 1
	v_add3_u32 v72, v214, v72, s33
	ds_write_b16_d16_hi v145, v72 offset:576
	v_bfe_u32 v72, v215, 16, 1
	v_add3_u32 v72, v215, v72, s33
	ds_write_b16_d16_hi v145, v72 offset:648
	v_bfe_u32 v72, v216, 16, 1
	v_add3_u32 v72, v216, v72, s33
	ds_write_b16_d16_hi v145, v72 offset:720
	v_bfe_u32 v72, v217, 16, 1
	v_add3_u32 v72, v217, v72, s33
	ds_write_b16_d16_hi v145, v72 offset:792
	s_waitcnt vmcnt(4)
	v_bfe_u32 v72, v218, 16, 1
	v_add3_u32 v72, v218, v72, s33
	ds_write_b16_d16_hi v145, v72 offset:864
	v_bfe_u32 v72, v219, 16, 1
	v_add3_u32 v72, v219, v72, s33
	ds_write_b16_d16_hi v145, v72 offset:936
	v_bfe_u32 v72, v220, 16, 1
	v_add3_u32 v72, v220, v72, s33
	ds_write_b16_d16_hi v145, v72 offset:1008
	v_bfe_u32 v72, v221, 16, 1
	v_add3_u32 v72, v221, v72, s33
	ds_write_b16_d16_hi v145, v72 offset:1080
	s_waitcnt vmcnt(3)
	v_bfe_u32 v72, v222, 16, 1
	v_add3_u32 v72, v222, v72, s33
	ds_write_b16_d16_hi v145, v72 offset:1152
	v_bfe_u32 v72, v223, 16, 1
	v_add3_u32 v72, v223, v72, s33
	ds_write_b16_d16_hi v145, v72 offset:1224
	v_bfe_u32 v72, v224, 16, 1
	v_add3_u32 v72, v224, v72, s33
	ds_write_b16_d16_hi v145, v72 offset:1296
	v_bfe_u32 v72, v225, 16, 1
	v_add3_u32 v72, v225, v72, s33
	ds_write_b16_d16_hi v145, v72 offset:1368
	s_waitcnt vmcnt(2)
	v_bfe_u32 v72, v226, 16, 1
	v_add3_u32 v72, v226, v72, s33
	ds_write_b16_d16_hi v145, v72 offset:1440
	v_bfe_u32 v72, v227, 16, 1
	v_add3_u32 v72, v227, v72, s33
	ds_write_b16_d16_hi v145, v72 offset:1512
	v_bfe_u32 v72, v228, 16, 1
	v_add3_u32 v72, v228, v72, s33
	ds_write_b16_d16_hi v145, v72 offset:1584
	v_bfe_u32 v72, v229, 16, 1
	v_add3_u32 v72, v229, v72, s33
	ds_write_b16_d16_hi v145, v72 offset:1656
	s_waitcnt vmcnt(1)
	v_bfe_u32 v72, v230, 16, 1
	v_add3_u32 v72, v230, v72, s33
	ds_write_b16_d16_hi v145, v72 offset:1728
	v_bfe_u32 v72, v231, 16, 1
	v_add3_u32 v72, v231, v72, s33
	ds_write_b16_d16_hi v145, v72 offset:1800
	v_bfe_u32 v72, v232, 16, 1
	v_add3_u32 v72, v232, v72, s33
	ds_write_b16_d16_hi v145, v72 offset:1872
	v_bfe_u32 v72, v233, 16, 1
	v_add3_u32 v72, v233, v72, s33
	ds_write_b16_d16_hi v145, v72 offset:1944
	s_waitcnt vmcnt(0)
	v_bfe_u32 v72, v234, 16, 1
	v_add3_u32 v72, v234, v72, s33
	ds_write_b16_d16_hi v145, v72 offset:2016
	v_bfe_u32 v72, v235, 16, 1
	v_add3_u32 v72, v235, v72, s33
	ds_write_b16_d16_hi v145, v72 offset:2088
	v_bfe_u32 v72, v236, 16, 1
	v_add3_u32 v72, v236, v72, s33
	ds_write_b16_d16_hi v145, v72 offset:2160
	v_bfe_u32 v72, v237, 16, 1
	v_add3_u32 v66, v237, v72, s33
	v_lshrrev_b32_e32 v66, 16, v66
.LBB0_864:
	s_andn2_b64 vcc, exec, s[0:1]
	s_cbranch_vccnz .LBB0_870
	s_waitcnt vmcnt(0)
	v_mov_b32_e32 v54, v190
	v_mov_b32_e32 v55, v191
	v_mov_b32_e32 v56, v192
	v_mov_b32_e32 v57, v193
	v_mov_b32_e32 v58, v194
	v_mov_b32_e32 v59, v195
	v_mov_b32_e32 v60, v196
	v_mov_b32_e32 v61, v197
	v_mov_b32_e32 v62, v198
	v_mov_b32_e32 v63, v199
	v_mov_b32_e32 v64, v200
	v_mov_b32_e32 v65, v201
	v_mov_b32_e32 v50, v202
	v_mov_b32_e32 v51, v203
	v_mov_b32_e32 v52, v204
	v_mov_b32_e32 v53, v205
	ds_write_b16 v145, v174
	ds_write_b16_d16_hi v145, v174 offset:72
	ds_write_b16 v145, v175 offset:144
	ds_write_b16_d16_hi v145, v175 offset:216
	ds_write_b16 v145, v176 offset:288
	ds_write_b16_d16_hi v145, v176 offset:360
	ds_write_b16 v145, v177 offset:432
	ds_write_b16_d16_hi v145, v177 offset:504
	ds_write_b16 v145, v178 offset:576
	ds_write_b16_d16_hi v145, v178 offset:648
	ds_write_b16 v145, v179 offset:720
	ds_write_b16_d16_hi v145, v179 offset:792
	ds_write_b16 v145, v180 offset:864
	ds_write_b16_d16_hi v145, v180 offset:936
	ds_write_b16 v145, v181 offset:1008
	ds_write_b16_d16_hi v145, v181 offset:1080
	ds_write_b16 v145, v182 offset:1152
	ds_write_b16_d16_hi v145, v182 offset:1224
	ds_write_b16 v145, v183 offset:1296
	ds_write_b16_d16_hi v145, v183 offset:1368
	ds_write_b16 v145, v184 offset:1440
	ds_write_b16_d16_hi v145, v184 offset:1512
	ds_write_b16 v145, v185 offset:1584
	ds_write_b16_d16_hi v145, v185 offset:1656
	ds_write_b16 v145, v186 offset:1728
	ds_write_b16_d16_hi v145, v186 offset:1800
	ds_write_b16 v145, v187 offset:1872
	ds_write_b16_d16_hi v145, v187 offset:1944
	ds_write_b16 v145, v188 offset:2016
	ds_write_b16_d16_hi v145, v188 offset:2088
	ds_write_b16 v145, v189 offset:2160
	v_lshrrev_b32_e32 v66, 16, v189
	s_cmp_gt_u32 s27, 1
	s_cbranch_scc0 .Lpf_nonext
	v_lshl_add_u64 v[206:207], v[206:207], 0, v[216:217]
	v_lshl_add_u64 v[208:209], v[208:209], 0, v[216:217]
	v_lshl_add_u64 v[210:211], v[210:211], 0, v[216:217]
	v_lshl_add_u64 v[212:213], v[212:213], 0, v[216:217]
	global_load_dwordx4 v[174:177], v[206:207], off offset:2048
	global_load_dwordx4 v[178:181], v[206:207], off offset:2064
	global_load_dwordx4 v[182:185], v[206:207], off offset:2080
	global_load_dwordx4 v[186:189], v[206:207], off offset:2096
	global_load_dwordx4 v[190:193], v[208:209], off offset:1024
	global_load_dwordx4 v[194:197], v[208:209], off offset:1088
	global_load_dwordx4 v[198:201], v[210:211], off offset:1024
	global_load_dwordx4 v[202:205], v[212:213], off offset:64
.Lpf_nonext:
.LBB0_870:
	ds_write_b16 v145, v66 offset:2232
	v_mfma_f32_16x16x32_bf16 v[66:69], v[54:57], v[2:5], 0
	v_cmp_lt_i32_e32 vcc, 0, v99
	v_mfma_f32_16x16x32_bf16 v[86:89], v[58:61], v[6:9], v[66:69]
	v_mfma_f32_16x16x32_bf16 v[66:69], v[62:65], v[2:5], 0
	v_mfma_f32_16x16x32_bf16 v[82:85], v[50:53], v[6:9], v[66:69]
	s_nop 5
	v_exp_f32_e64 v67, -|v86|
	v_max_f32_e32 v66, v86, v86
	v_max_f32_e32 v66, 0, v66
	v_add_f32_e32 v67, 1.0, v67
	v_log_f32_e32 v67, v67
	s_nop 0
	v_add_f32_e32 v159, v66, v67
	v_exp_f32_e64 v67, -|v87|
	v_max_f32_e32 v66, v87, v87
	v_max_f32_e32 v66, 0, v66
	v_add_f32_e32 v67, 1.0, v67
	v_log_f32_e32 v67, v67
	s_nop 0
	v_add_f32_e32 v160, v66, v67
	v_exp_f32_e64 v67, -|v88|
	v_max_f32_e32 v66, v88, v88
	v_max_f32_e32 v66, 0, v66
	v_add_f32_e32 v67, 1.0, v67
	v_log_f32_e32 v67, v67
	s_nop 0
	v_add_f32_e32 v161, v66, v67
	v_exp_f32_e64 v67, -|v89|
	v_max_f32_e32 v66, v89, v89
	v_max_f32_e32 v66, 0, v66
	v_add_f32_e32 v67, 1.0, v67
	v_log_f32_e32 v67, v67
	s_nop 0
	v_add_f32_e32 v163, v66, v67
	v_add_f32_e32 v164, v163, v161
	v_add_f32_e32 v165, v160, v164
	ds_read2_b64 v[74:77], v107 offset1:4
	ds_read2_b64 v[78:81], v119 offset1:4
	ds_read2_b64 v[70:73], v154 offset0:33 offset1:37
	ds_read2_b64 v[66:69], v154 offset0:177 offset1:181
	v_add_f32_e32 v90, v159, v165
	ds_bpermute_b32 v157, v133, v90
	ds_bpermute_b32 v156, v135, v90
	ds_bpermute_b32 v158, v153, v90
	s_and_saveexec_b64 s[0:1], vcc
	s_xor_b64 s[0:1], exec, s[0:1]
	s_cbranch_execz .LBB0_876
	v_cmp_ne_u32_e32 vcc, 1, v99
	s_and_saveexec_b64 s[2:3], vcc
	s_xor_b64 s[2:3], exec, s[2:3]
	s_cbranch_execz .LBB0_873
	s_waitcnt lgkmcnt(2)
	v_cndmask_b32_e64 v166, 0, v157, s[6:7]

.LBB0_997:
	ds_read_b128 v[142:145], v168
	ds_read_b128 v[146:149], v169
	ds_read_b128 v[150:153], v170
	ds_read_b128 v[154:157], v171
	s_add_i32 s57, s2, 2
	s_add_u32 s26, s24, 0x80
	s_addc_u32 s3, s25, 0
	s_cmp_eq_u32 s46, s2
	s_cselect_b32 s2, s10, s26
	s_cselect_b32 s3, s11, s3
	s_cselect_b32 s27, s1, s37
	s_cselect_b32 s26, s0, s36
	s_mov_b32 m0, s51
	v_lshl_add_u64 v[158:159], s[24:25], 0, v[134:135]
	ds_read_b128 v[186:189], v166
	ds_read_b128 v[190:193], v166 offset:1024
	ds_read_b128 v[194:197], v166 offset:2048
	ds_read_b128 v[198:201], v166 offset:3072
	ds_read_b128 v[202:205], v166 offset:4096
	ds_read_b128 v[206:209], v166 offset:5120
	ds_read_b128 v[210:213], v166 offset:6144
	ds_read_b128 v[214:217], v166 offset:7168
	global_load_lds_dwordx4 v[158:159], off
	v_lshl_add_u64 v[158:159], s[24:25], 0, v[136:137]
	s_mov_b32 m0, s52
	s_nop 0
	global_load_lds_dwordx4 v[158:159], off
	s_waitcnt lgkmcnt(8)
	s_barrier
	s_waitcnt lgkmcnt(0)
	s_setprio 1
	s_waitcnt lgkmcnt(0)
	v_mfma_f32_16x16x32_bf16 v[126:129], v[142:145], v[186:189], v[126:129]
	v_mfma_f32_16x16x32_bf16 v[122:125], v[150:153], v[186:189], v[122:125]
	v_mfma_f32_16x16x32_bf16 v[110:113], v[142:145], v[194:197], v[110:113]
	v_mfma_f32_16x16x32_bf16 v[106:109], v[150:153], v[194:197], v[106:109]
	v_mfma_f32_16x16x32_bf16 v[94:97], v[142:145], v[202:205], v[94:97]
	v_mfma_f32_16x16x32_bf16 v[90:93], v[150:153], v[202:205], v[90:93]
	v_mfma_f32_16x16x32_bf16 v[78:81], v[142:145], v[210:213], v[78:81]
	v_mfma_f32_16x16x32_bf16 v[74:77], v[150:153], v[210:213], v[74:77]
	v_mfma_f32_16x16x32_bf16 v[126:129], v[146:149], v[190:193], v[126:129]
	v_mfma_f32_16x16x32_bf16 v[122:125], v[154:157], v[190:193], v[122:125]
	v_mfma_f32_16x16x32_bf16 v[110:113], v[146:149], v[198:201], v[110:113]
	v_mfma_f32_16x16x32_bf16 v[106:109], v[154:157], v[198:201], v[106:109]
	v_mfma_f32_16x16x32_bf16 v[94:97], v[146:149], v[206:209], v[94:97]
	v_mfma_f32_16x16x32_bf16 v[90:93], v[154:157], v[206:209], v[90:93]
	v_mfma_f32_16x16x32_bf16 v[78:81], v[146:149], v[214:217], v[78:81]
	v_mfma_f32_16x16x32_bf16 v[74:77], v[154:157], v[214:217], v[74:77]
	s_setprio 0
	s_barrier
	s_mov_b32 m0, s29
	v_lshl_add_u64 v[158:159], s[26:27], 0, v[130:131]
	ds_read_b128 v[218:221], v172
	ds_read_b128 v[222:225], v173
	ds_read_b128 v[226:229], v174
	ds_read_b128 v[230:233], v175
	global_load_lds_dwordx4 v[158:159], off
	v_lshl_add_u64 v[234:235], s[26:27], 0, v[132:133]
	s_mov_b32 m0, s30
	s_nop 0
	global_load_lds_dwordx4 v[234:235], off
	s_barrier
	s_waitcnt lgkmcnt(0)
	s_setprio 1
	s_waitcnt lgkmcnt(0)
	v_mfma_f32_16x16x32_bf16 v[118:121], v[218:221], v[186:189], v[118:121]
	v_mfma_f32_16x16x32_bf16 v[114:117], v[226:229], v[186:189], v[114:117]
	v_mfma_f32_16x16x32_bf16 v[102:105], v[218:221], v[194:197], v[102:105]
	v_mfma_f32_16x16x32_bf16 v[98:101], v[226:229], v[194:197], v[98:101]
	v_mfma_f32_16x16x32_bf16 v[86:89], v[218:221], v[202:205], v[86:89]
	v_mfma_f32_16x16x32_bf16 v[82:85], v[226:229], v[202:205], v[82:85]
	v_mfma_f32_16x16x32_bf16 v[70:73], v[218:221], v[210:213], v[70:73]
	v_mfma_f32_16x16x32_bf16 v[66:69], v[226:229], v[210:213], v[66:69]
	v_mfma_f32_16x16x32_bf16 v[118:121], v[222:225], v[190:193], v[118:121]
	v_mfma_f32_16x16x32_bf16 v[114:117], v[230:233], v[190:193], v[114:117]
	v_mfma_f32_16x16x32_bf16 v[102:105], v[222:225], v[198:201], v[102:105]
	v_mfma_f32_16x16x32_bf16 v[98:101], v[230:233], v[198:201], v[98:101]
	v_mfma_f32_16x16x32_bf16 v[86:89], v[222:225], v[206:209], v[86:89]
	v_mfma_f32_16x16x32_bf16 v[82:85], v[230:233], v[206:209], v[82:85]
	v_mfma_f32_16x16x32_bf16 v[70:73], v[222:225], v[214:217], v[70:73]
	v_mfma_f32_16x16x32_bf16 v[66:69], v[230:233], v[214:217], v[66:69]
	s_setprio 0
	s_mov_b32 m0, s28
	v_lshl_add_u64 v[236:237], s[2:3], 0, v[130:131]
	s_barrier
	ds_read_b128 v[186:189], v166 offset:16384
	ds_read_b128 v[190:193], v166 offset:17408
	ds_read_b128 v[194:197], v166 offset:18432
	ds_read_b128 v[198:201], v166 offset:19456
	ds_read_b128 v[202:205], v166 offset:20480
	ds_read_b128 v[206:209], v166 offset:21504
	ds_read_b128 v[210:213], v166 offset:22528
	ds_read_b128 v[214:217], v166 offset:23552
	global_load_lds_dwordx4 v[236:237], off
	v_lshl_add_u64 v[238:239], s[2:3], 0, v[132:133]
	s_mov_b32 m0, s31
	s_nop 0
	global_load_lds_dwordx4 v[238:239], off
	s_barrier
	s_waitcnt lgkmcnt(0)
	s_setprio 1
	s_waitcnt lgkmcnt(0)
	v_mfma_f32_16x16x32_bf16 v[62:65], v[142:145], v[186:189], v[62:65]
	v_mfma_f32_16x16x32_bf16 v[58:61], v[150:153], v[186:189], v[58:61]
	v_mfma_f32_16x16x32_bf16 v[46:49], v[142:145], v[194:197], v[46:49]
	v_mfma_f32_16x16x32_bf16 v[42:45], v[150:153], v[194:197], v[42:45]
	v_mfma_f32_16x16x32_bf16 v[30:33], v[142:145], v[202:205], v[30:33]
	v_mfma_f32_16x16x32_bf16 v[26:29], v[150:153], v[202:205], v[26:29]
	v_mfma_f32_16x16x32_bf16 v[14:17], v[142:145], v[210:213], v[14:17]
	v_mfma_f32_16x16x32_bf16 v[10:13], v[150:153], v[210:213], v[10:13]
	v_mfma_f32_16x16x32_bf16 v[62:65], v[146:149], v[190:193], v[62:65]
	v_mfma_f32_16x16x32_bf16 v[58:61], v[154:157], v[190:193], v[58:61]
	v_mfma_f32_16x16x32_bf16 v[46:49], v[146:149], v[198:201], v[46:49]
	v_mfma_f32_16x16x32_bf16 v[42:45], v[154:157], v[198:201], v[42:45]
	v_mfma_f32_16x16x32_bf16 v[30:33], v[146:149], v[206:209], v[30:33]
	v_mfma_f32_16x16x32_bf16 v[26:29], v[154:157], v[206:209], v[26:29]
	v_mfma_f32_16x16x32_bf16 v[14:17], v[146:149], v[214:217], v[14:17]
	v_mfma_f32_16x16x32_bf16 v[10:13], v[154:157], v[214:217], v[10:13]
	s_setprio 0
	s_barrier
	s_add_u32 s26, s26, s16
	s_addc_u32 s27, s27, s17
	s_mov_b32 m0, s33
	v_lshl_add_u64 v[240:241], s[26:27], 0, v[130:131]
	global_load_lds_dwordx4 v[240:241], off
	v_lshl_add_u64 v[242:243], s[26:27], 0, v[132:133]
	s_mov_b32 m0, s34
	s_nop 0
	global_load_lds_dwordx4 v[242:243], off
	s_waitcnt vmcnt(6)
	s_barrier
	s_setprio 1
	v_mfma_f32_16x16x32_bf16 v[54:57], v[218:221], v[186:189], v[54:57]
	v_mfma_f32_16x16x32_bf16 v[50:53], v[226:229], v[186:189], v[50:53]
	v_mfma_f32_16x16x32_bf16 v[38:41], v[218:221], v[194:197], v[38:41]
	v_mfma_f32_16x16x32_bf16 v[34:37], v[226:229], v[194:197], v[34:37]
	v_mfma_f32_16x16x32_bf16 v[22:25], v[218:221], v[202:205], v[22:25]
	v_mfma_f32_16x16x32_bf16 v[18:21], v[226:229], v[202:205], v[18:21]
	v_mfma_f32_16x16x32_bf16 v[6:9], v[218:221], v[210:213], v[6:9]
	v_mfma_f32_16x16x32_bf16 v[2:5], v[226:229], v[210:213], v[2:5]
	v_mfma_f32_16x16x32_bf16 v[54:57], v[222:225], v[190:193], v[54:57]
	v_mfma_f32_16x16x32_bf16 v[50:53], v[230:233], v[190:193], v[50:53]
	v_mfma_f32_16x16x32_bf16 v[38:41], v[222:225], v[198:201], v[38:41]
	v_mfma_f32_16x16x32_bf16 v[34:37], v[230:233], v[198:201], v[34:37]
	v_mfma_f32_16x16x32_bf16 v[22:25], v[222:225], v[206:209], v[22:25]
	v_mfma_f32_16x16x32_bf16 v[18:21], v[230:233], v[206:209], v[18:21]
	v_mfma_f32_16x16x32_bf16 v[6:9], v[222:225], v[214:217], v[6:9]
	v_mfma_f32_16x16x32_bf16 v[2:5], v[230:233], v[214:217], v[2:5]
	s_setprio 0
	s_barrier
	ds_read_b128 v[142:145], v176
	ds_read_b128 v[146:149], v177
	ds_read_b128 v[150:153], v178
	ds_read_b128 v[154:157], v179
	s_add_u32 s2, s2, s16
	s_addc_u32 s3, s3, s17
	s_mov_b32 m0, s35
	v_lshl_add_u64 v[218:219], s[2:3], 0, v[130:131]
	ds_read_b128 v[186:189], v166 offset:32768
	ds_read_b128 v[190:193], v166 offset:33792
	ds_read_b128 v[194:197], v166 offset:34816
	ds_read_b128 v[198:201], v166 offset:35840
	ds_read_b128 v[202:205], v166 offset:36864
	ds_read_b128 v[206:209], v166 offset:37888
	ds_read_b128 v[210:213], v166 offset:38912
	ds_read_b128 v[214:217], v166 offset:39936
	global_load_lds_dwordx4 v[218:219], off
	v_lshl_add_u64 v[218:219], s[2:3], 0, v[132:133]
	s_mov_b32 m0, s38
	s_nop 0
	global_load_lds_dwordx4 v[218:219], off
	s_waitcnt lgkmcnt(8)
	s_barrier
	s_waitcnt lgkmcnt(0)
	s_setprio 1
	s_waitcnt lgkmcnt(0)
	v_mfma_f32_16x16x32_bf16 v[126:129], v[142:145], v[186:189], v[126:129]
	v_mfma_f32_16x16x32_bf16 v[122:125], v[150:153], v[186:189], v[122:125]
	v_mfma_f32_16x16x32_bf16 v[110:113], v[142:145], v[194:197], v[110:113]
	v_mfma_f32_16x16x32_bf16 v[106:109], v[150:153], v[194:197], v[106:109]
	v_mfma_f32_16x16x32_bf16 v[94:97], v[142:145], v[202:205], v[94:97]
	v_mfma_f32_16x16x32_bf16 v[90:93], v[150:153], v[202:205], v[90:93]
	v_mfma_f32_16x16x32_bf16 v[78:81], v[142:145], v[210:213], v[78:81]
	v_mfma_f32_16x16x32_bf16 v[74:77], v[150:153], v[210:213], v[74:77]
	v_mfma_f32_16x16x32_bf16 v[126:129], v[146:149], v[190:193], v[126:129]
	v_mfma_f32_16x16x32_bf16 v[122:125], v[154:157], v[190:193], v[122:125]
	v_mfma_f32_16x16x32_bf16 v[110:113], v[146:149], v[198:201], v[110:113]
	v_mfma_f32_16x16x32_bf16 v[106:109], v[154:157], v[198:201], v[106:109]
	v_mfma_f32_16x16x32_bf16 v[94:97], v[146:149], v[206:209], v[94:97]
	v_mfma_f32_16x16x32_bf16 v[90:93], v[154:157], v[206:209], v[90:93]
	v_mfma_f32_16x16x32_bf16 v[78:81], v[146:149], v[214:217], v[78:81]
	v_mfma_f32_16x16x32_bf16 v[74:77], v[154:157], v[214:217], v[74:77]
	s_setprio 0
	s_barrier
	s_mov_b32 m0, s39
	v_lshl_add_u64 v[158:159], v[158:159], 0, s[20:21]
	ds_read_b128 v[218:221], v180
	ds_read_b128 v[222:225], v181
	ds_read_b128 v[226:229], v182
	ds_read_b128 v[230:233], v183
	global_load_lds_dwordx4 v[158:159], off
	v_lshl_add_u64 v[158:159], v[234:235], 0, s[20:21]
	s_mov_b32 m0, s40
	s_nop 0
	global_load_lds_dwordx4 v[158:159], off
	s_barrier
	s_waitcnt lgkmcnt(0)
	s_setprio 1
	s_waitcnt lgkmcnt(0)
	v_mfma_f32_16x16x32_bf16 v[118:121], v[218:221], v[186:189], v[118:121]
	v_mfma_f32_16x16x32_bf16 v[114:117], v[226:229], v[186:189], v[114:117]
	v_mfma_f32_16x16x32_bf16 v[102:105], v[218:221], v[194:197], v[102:105]
	v_mfma_f32_16x16x32_bf16 v[98:101], v[226:229], v[194:197], v[98:101]
	v_mfma_f32_16x16x32_bf16 v[86:89], v[218:221], v[202:205], v[86:89]
	v_mfma_f32_16x16x32_bf16 v[82:85], v[226:229], v[202:205], v[82:85]
	v_mfma_f32_16x16x32_bf16 v[70:73], v[218:221], v[210:213], v[70:73]
	v_mfma_f32_16x16x32_bf16 v[66:69], v[226:229], v[210:213], v[66:69]
	v_mfma_f32_16x16x32_bf16 v[118:121], v[222:225], v[190:193], v[118:121]
	v_mfma_f32_16x16x32_bf16 v[114:117], v[230:233], v[190:193], v[114:117]
	v_mfma_f32_16x16x32_bf16 v[102:105], v[222:225], v[198:201], v[102:105]
	v_mfma_f32_16x16x32_bf16 v[98:101], v[230:233], v[198:201], v[98:101]
	v_mfma_f32_16x16x32_bf16 v[86:89], v[222:225], v[206:209], v[86:89]
	v_mfma_f32_16x16x32_bf16 v[82:85], v[230:233], v[206:209], v[82:85]
	v_mfma_f32_16x16x32_bf16 v[70:73], v[222:225], v[214:217], v[70:73]
	v_mfma_f32_16x16x32_bf16 v[66:69], v[230:233], v[214:217], v[66:69]
	s_setprio 0
	s_mov_b32 m0, s41
	v_lshl_add_u64 v[158:159], v[236:237], 0, s[20:21]
	s_barrier
	ds_read_b128 v[186:189], v166 offset:49152
	ds_read_b128 v[190:193], v166 offset:50176
	ds_read_b128 v[194:197], v166 offset:51200
	ds_read_b128 v[198:201], v166 offset:52224
	ds_read_b128 v[202:205], v166 offset:53248
	ds_read_b128 v[206:209], v166 offset:54272
	ds_read_b128 v[210:213], v166 offset:55296
	ds_read_b128 v[214:217], v166 offset:56320
	global_load_lds_dwordx4 v[158:159], off
	v_lshl_add_u64 v[158:159], v[238:239], 0, s[20:21]
	s_mov_b32 m0, s42
	s_nop 0
	global_load_lds_dwordx4 v[158:159], off
	s_barrier
	s_waitcnt lgkmcnt(0)
	s_setprio 1
	s_waitcnt lgkmcnt(0)
	v_mfma_f32_16x16x32_bf16 v[62:65], v[142:145], v[186:189], v[62:65]
	v_mfma_f32_16x16x32_bf16 v[58:61], v[150:153], v[186:189], v[58:61]
	v_mfma_f32_16x16x32_bf16 v[46:49], v[142:145], v[194:197], v[46:49]
	v_mfma_f32_16x16x32_bf16 v[42:45], v[150:153], v[194:197], v[42:45]
	v_mfma_f32_16x16x32_bf16 v[30:33], v[142:145], v[202:205], v[30:33]
	v_mfma_f32_16x16x32_bf16 v[26:29], v[150:153], v[202:205], v[26:29]
	v_mfma_f32_16x16x32_bf16 v[14:17], v[142:145], v[210:213], v[14:17]
	v_mfma_f32_16x16x32_bf16 v[10:13], v[150:153], v[210:213], v[10:13]
	v_mfma_f32_16x16x32_bf16 v[62:65], v[146:149], v[190:193], v[62:65]
	v_mfma_f32_16x16x32_bf16 v[58:61], v[154:157], v[190:193], v[58:61]
	v_mfma_f32_16x16x32_bf16 v[46:49], v[146:149], v[198:201], v[46:49]
	v_mfma_f32_16x16x32_bf16 v[42:45], v[154:157], v[198:201], v[42:45]
	v_mfma_f32_16x16x32_bf16 v[30:33], v[146:149], v[206:209], v[30:33]
	v_mfma_f32_16x16x32_bf16 v[26:29], v[154:157], v[206:209], v[26:29]
	v_mfma_f32_16x16x32_bf16 v[14:17], v[146:149], v[214:217], v[14:17]
	v_mfma_f32_16x16x32_bf16 v[10:13], v[154:157], v[214:217], v[10:13]
	s_setprio 0
	s_barrier
	s_mov_b32 m0, s43
	v_lshl_add_u64 v[142:143], v[240:241], 0, s[20:21]
	global_load_lds_dwordx4 v[142:143], off
	v_lshl_add_u64 v[142:143], v[242:243], 0, s[20:21]
	s_mov_b32 m0, s44
	s_nop 0
	global_load_lds_dwordx4 v[142:143], off
	s_waitcnt vmcnt(6)
	s_barrier
	s_setprio 1
	v_mfma_f32_16x16x32_bf16 v[54:57], v[218:221], v[186:189], v[54:57]
	v_mfma_f32_16x16x32_bf16 v[50:53], v[226:229], v[186:189], v[50:53]
	v_mfma_f32_16x16x32_bf16 v[38:41], v[218:221], v[194:197], v[38:41]
	v_mfma_f32_16x16x32_bf16 v[34:37], v[226:229], v[194:197], v[34:37]
	v_mfma_f32_16x16x32_bf16 v[22:25], v[218:221], v[202:205], v[22:25]
	v_mfma_f32_16x16x32_bf16 v[18:21], v[226:229], v[202:205], v[18:21]
	v_mfma_f32_16x16x32_bf16 v[6:9], v[218:221], v[210:213], v[6:9]
	v_mfma_f32_16x16x32_bf16 v[2:5], v[226:229], v[210:213], v[2:5]
	v_mfma_f32_16x16x32_bf16 v[54:57], v[222:225], v[190:193], v[54:57]
	v_mfma_f32_16x16x32_bf16 v[50:53], v[230:233], v[190:193], v[50:53]
	v_mfma_f32_16x16x32_bf16 v[38:41], v[222:225], v[198:201], v[38:41]
	v_mfma_f32_16x16x32_bf16 v[34:37], v[230:233], v[198:201], v[34:37]
	v_mfma_f32_16x16x32_bf16 v[22:25], v[222:225], v[206:209], v[22:25]
	v_mfma_f32_16x16x32_bf16 v[18:21], v[230:233], v[206:209], v[18:21]
	v_mfma_f32_16x16x32_bf16 v[6:9], v[222:225], v[214:217], v[6:9]
	v_mfma_f32_16x16x32_bf16 v[2:5], v[230:233], v[214:217], v[2:5]
	s_setprio 0
	s_add_u32 s24, s24, 0x100
	s_addc_u32 s25, s25, 0
	s_add_u32 s36, s36, 0x100
	s_addc_u32 s37, s37, 0
	s_cmp_ge_i32 s57, s45
	s_mov_b32 s2, s57
	s_barrier
	s_cbranch_scc0 .LBB0_997

.LBB0_1104:
	ds_read_b128 v[122:125], v185
	ds_read_b128 v[126:129], v186
	ds_read_b128 v[138:141], v187
	ds_read_b128 v[142:145], v188
	s_add_i32 s36, s2, 2
	s_add_u32 s26, s0, 0x80
	s_addc_u32 s3, s1, 0
	s_cmp_eq_u32 s58, s2
	s_cselect_b32 s2, s8, s26
	s_cselect_b32 s3, s9, s3
	s_cselect_b32 s27, s55, s29
	s_cselect_b32 s26, s54, s28
	s_mov_b32 m0, s61
	v_lshl_add_u64 v[214:215], s[0:1], 0, v[168:169]
	ds_read_b128 v[146:149], v183
	ds_read_b128 v[150:153], v183 offset:1024
	ds_read_b128 v[154:157], v183 offset:2048
	ds_read_b128 v[158:161], v183 offset:3072
	ds_read_b128 v[176:179], v183 offset:4096
	ds_read_b128 v[202:205], v183 offset:5120
	ds_read_b128 v[206:209], v183 offset:6144
	ds_read_b128 v[210:213], v183 offset:7168
	global_load_lds_dwordx4 v[214:215], off
	v_lshl_add_u64 v[214:215], s[0:1], 0, v[170:171]
	s_mov_b32 m0, s62
	s_nop 0
	global_load_lds_dwordx4 v[214:215], off
	s_waitcnt lgkmcnt(8)
	s_barrier
	s_waitcnt lgkmcnt(0)
	s_setprio 1
	s_waitcnt lgkmcnt(0)
	v_mfma_f32_16x16x32_bf16 v[134:137], v[122:125], v[146:149], v[134:137]
	v_mfma_f32_16x16x32_bf16 v[118:121], v[138:141], v[146:149], v[118:121]
	v_mfma_f32_16x16x32_bf16 v[110:113], v[122:125], v[154:157], v[110:113]
	v_mfma_f32_16x16x32_bf16 v[102:105], v[138:141], v[154:157], v[102:105]
	v_mfma_f32_16x16x32_bf16 v[94:97], v[122:125], v[176:179], v[94:97]
	v_mfma_f32_16x16x32_bf16 v[86:89], v[138:141], v[176:179], v[86:89]
	v_mfma_f32_16x16x32_bf16 v[78:81], v[122:125], v[206:209], v[78:81]
	v_mfma_f32_16x16x32_bf16 v[70:73], v[138:141], v[206:209], v[70:73]
	v_mfma_f32_16x16x32_bf16 v[134:137], v[126:129], v[150:153], v[134:137]
	v_mfma_f32_16x16x32_bf16 v[118:121], v[142:145], v[150:153], v[118:121]
	v_mfma_f32_16x16x32_bf16 v[110:113], v[126:129], v[158:161], v[110:113]
	v_mfma_f32_16x16x32_bf16 v[102:105], v[142:145], v[158:161], v[102:105]
	v_mfma_f32_16x16x32_bf16 v[94:97], v[126:129], v[202:205], v[94:97]
	v_mfma_f32_16x16x32_bf16 v[86:89], v[142:145], v[202:205], v[86:89]
	v_mfma_f32_16x16x32_bf16 v[78:81], v[126:129], v[210:213], v[78:81]
	v_mfma_f32_16x16x32_bf16 v[70:73], v[142:145], v[210:213], v[70:73]
	s_setprio 0
	s_barrier
	s_mov_b32 m0, s35
	v_lshl_add_u64 v[230:231], s[26:27], 0, v[166:167]
	ds_read_b128 v[214:217], v189
	ds_read_b128 v[218:221], v190
	ds_read_b128 v[222:225], v191
	ds_read_b128 v[226:229], v192
	global_load_lds_dwordx4 v[230:231], off
	v_lshl_add_u64 v[232:233], s[26:27], 0, v[164:165]
	s_mov_b32 m0, s38
	s_nop 0
	global_load_lds_dwordx4 v[232:233], off
	s_barrier
	s_waitcnt lgkmcnt(0)
	s_setprio 1
	s_waitcnt lgkmcnt(0)
	v_mfma_f32_16x16x32_bf16 v[130:133], v[214:217], v[146:149], v[130:133]
	v_mfma_f32_16x16x32_bf16 v[114:117], v[222:225], v[146:149], v[114:117]
	v_mfma_f32_16x16x32_bf16 v[106:109], v[214:217], v[154:157], v[106:109]
	v_mfma_f32_16x16x32_bf16 v[98:101], v[222:225], v[154:157], v[98:101]
	v_mfma_f32_16x16x32_bf16 v[90:93], v[214:217], v[176:179], v[90:93]
	v_mfma_f32_16x16x32_bf16 v[82:85], v[222:225], v[176:179], v[82:85]
	v_mfma_f32_16x16x32_bf16 v[74:77], v[214:217], v[206:209], v[74:77]
	v_mfma_f32_16x16x32_bf16 v[66:69], v[222:225], v[206:209], v[66:69]
	v_mfma_f32_16x16x32_bf16 v[130:133], v[218:221], v[150:153], v[130:133]
	v_mfma_f32_16x16x32_bf16 v[114:117], v[226:229], v[150:153], v[114:117]
	v_mfma_f32_16x16x32_bf16 v[106:109], v[218:221], v[158:161], v[106:109]
	v_mfma_f32_16x16x32_bf16 v[98:101], v[226:229], v[158:161], v[98:101]
	v_mfma_f32_16x16x32_bf16 v[90:93], v[218:221], v[202:205], v[90:93]
	v_mfma_f32_16x16x32_bf16 v[82:85], v[226:229], v[202:205], v[82:85]
	v_mfma_f32_16x16x32_bf16 v[74:77], v[218:221], v[210:213], v[74:77]
	v_mfma_f32_16x16x32_bf16 v[66:69], v[226:229], v[210:213], v[66:69]
	s_setprio 0
	s_mov_b32 m0, s31
	v_lshl_add_u64 v[234:235], s[2:3], 0, v[166:167]
	s_barrier
	ds_read_b128 v[146:149], v183 offset:16384
	ds_read_b128 v[150:153], v183 offset:17408
	ds_read_b128 v[154:157], v183 offset:18432
	ds_read_b128 v[158:161], v183 offset:19456
	ds_read_b128 v[176:179], v183 offset:20480
	ds_read_b128 v[202:205], v183 offset:21504
	ds_read_b128 v[206:209], v183 offset:22528
	ds_read_b128 v[210:213], v183 offset:23552
	global_load_lds_dwordx4 v[234:235], off
	v_lshl_add_u64 v[236:237], s[2:3], 0, v[164:165]
	s_mov_b32 m0, s39
	s_nop 0
	global_load_lds_dwordx4 v[236:237], off
	s_barrier
	s_waitcnt lgkmcnt(0)
	s_setprio 1
	s_waitcnt lgkmcnt(0)
	v_mfma_f32_16x16x32_bf16 v[62:65], v[122:125], v[146:149], v[62:65]
	v_mfma_f32_16x16x32_bf16 v[54:57], v[138:141], v[146:149], v[54:57]
	v_mfma_f32_16x16x32_bf16 v[46:49], v[122:125], v[154:157], v[46:49]
	v_mfma_f32_16x16x32_bf16 v[38:41], v[138:141], v[154:157], v[38:41]
	v_mfma_f32_16x16x32_bf16 v[30:33], v[122:125], v[176:179], v[30:33]
	v_mfma_f32_16x16x32_bf16 v[22:25], v[138:141], v[176:179], v[22:25]
	v_mfma_f32_16x16x32_bf16 v[14:17], v[122:125], v[206:209], v[14:17]
	v_mfma_f32_16x16x32_bf16 v[6:9], v[138:141], v[206:209], v[6:9]
	v_mfma_f32_16x16x32_bf16 v[62:65], v[126:129], v[150:153], v[62:65]
	v_mfma_f32_16x16x32_bf16 v[54:57], v[142:145], v[150:153], v[54:57]
	v_mfma_f32_16x16x32_bf16 v[46:49], v[126:129], v[158:161], v[46:49]
	v_mfma_f32_16x16x32_bf16 v[38:41], v[142:145], v[158:161], v[38:41]
	v_mfma_f32_16x16x32_bf16 v[30:33], v[126:129], v[202:205], v[30:33]
	v_mfma_f32_16x16x32_bf16 v[22:25], v[142:145], v[202:205], v[22:25]
	v_mfma_f32_16x16x32_bf16 v[14:17], v[126:129], v[210:213], v[14:17]
	v_mfma_f32_16x16x32_bf16 v[6:9], v[142:145], v[210:213], v[6:9]
	s_setprio 0
	s_barrier
	s_add_u32 s26, s26, s22
	s_addc_u32 s27, s27, s23
	s_mov_b32 m0, s40
	v_lshl_add_u64 v[238:239], s[26:27], 0, v[166:167]
	global_load_lds_dwordx4 v[238:239], off
	v_lshl_add_u64 v[240:241], s[26:27], 0, v[164:165]
	s_mov_b32 m0, s41
	s_nop 0
	global_load_lds_dwordx4 v[240:241], off
	s_waitcnt vmcnt(6)
	s_barrier
	s_setprio 1
	v_mfma_f32_16x16x32_bf16 v[58:61], v[214:217], v[146:149], v[58:61]
	v_mfma_f32_16x16x32_bf16 v[50:53], v[222:225], v[146:149], v[50:53]
	v_mfma_f32_16x16x32_bf16 v[42:45], v[214:217], v[154:157], v[42:45]
	v_mfma_f32_16x16x32_bf16 v[34:37], v[222:225], v[154:157], v[34:37]
	v_mfma_f32_16x16x32_bf16 v[26:29], v[214:217], v[176:179], v[26:29]
	v_mfma_f32_16x16x32_bf16 v[18:21], v[222:225], v[176:179], v[18:21]
	v_mfma_f32_16x16x32_bf16 v[10:13], v[214:217], v[206:209], v[10:13]
	v_mfma_f32_16x16x32_bf16 v[2:5], v[222:225], v[206:209], v[2:5]
	v_mfma_f32_16x16x32_bf16 v[58:61], v[218:221], v[150:153], v[58:61]
	v_mfma_f32_16x16x32_bf16 v[50:53], v[226:229], v[150:153], v[50:53]
	v_mfma_f32_16x16x32_bf16 v[42:45], v[218:221], v[158:161], v[42:45]
	v_mfma_f32_16x16x32_bf16 v[34:37], v[226:229], v[158:161], v[34:37]
	v_mfma_f32_16x16x32_bf16 v[26:29], v[218:221], v[202:205], v[26:29]
	v_mfma_f32_16x16x32_bf16 v[18:21], v[226:229], v[202:205], v[18:21]
	v_mfma_f32_16x16x32_bf16 v[10:13], v[218:221], v[210:213], v[10:13]
	v_mfma_f32_16x16x32_bf16 v[2:5], v[226:229], v[210:213], v[2:5]
	s_setprio 0
	s_barrier
	ds_read_b128 v[122:125], v193
	ds_read_b128 v[126:129], v194
	ds_read_b128 v[138:141], v195
	ds_read_b128 v[142:145], v196
	s_add_u32 s2, s2, s22
	s_addc_u32 s3, s3, s23
	s_mov_b32 m0, s42
	v_lshl_add_u64 v[214:215], s[2:3], 0, v[166:167]
	ds_read_b128 v[146:149], v183 offset:32768
	ds_read_b128 v[150:153], v183 offset:33792
	ds_read_b128 v[154:157], v183 offset:34816
	ds_read_b128 v[158:161], v183 offset:35840
	ds_read_b128 v[176:179], v183 offset:36864
	ds_read_b128 v[202:205], v183 offset:37888
	ds_read_b128 v[206:209], v183 offset:38912
	ds_read_b128 v[210:213], v183 offset:39936
	global_load_lds_dwordx4 v[214:215], off
	v_lshl_add_u64 v[214:215], s[2:3], 0, v[164:165]
	s_mov_b32 m0, s43
	s_nop 0
	global_load_lds_dwordx4 v[214:215], off
	s_waitcnt lgkmcnt(8)
	s_barrier
	s_waitcnt lgkmcnt(0)
	s_setprio 1
	s_waitcnt lgkmcnt(0)
	v_mfma_f32_16x16x32_bf16 v[134:137], v[122:125], v[146:149], v[134:137]
	v_mfma_f32_16x16x32_bf16 v[118:121], v[138:141], v[146:149], v[118:121]
	v_mfma_f32_16x16x32_bf16 v[110:113], v[122:125], v[154:157], v[110:113]
	v_mfma_f32_16x16x32_bf16 v[102:105], v[138:141], v[154:157], v[102:105]
	v_mfma_f32_16x16x32_bf16 v[94:97], v[122:125], v[176:179], v[94:97]
	v_mfma_f32_16x16x32_bf16 v[86:89], v[138:141], v[176:179], v[86:89]
	v_mfma_f32_16x16x32_bf16 v[78:81], v[122:125], v[206:209], v[78:81]
	v_mfma_f32_16x16x32_bf16 v[70:73], v[138:141], v[206:209], v[70:73]
	v_mfma_f32_16x16x32_bf16 v[134:137], v[126:129], v[150:153], v[134:137]
	v_mfma_f32_16x16x32_bf16 v[118:121], v[142:145], v[150:153], v[118:121]
	v_mfma_f32_16x16x32_bf16 v[110:113], v[126:129], v[158:161], v[110:113]
	v_mfma_f32_16x16x32_bf16 v[102:105], v[142:145], v[158:161], v[102:105]
	v_mfma_f32_16x16x32_bf16 v[94:97], v[126:129], v[202:205], v[94:97]
	v_mfma_f32_16x16x32_bf16 v[86:89], v[142:145], v[202:205], v[86:89]
	v_mfma_f32_16x16x32_bf16 v[78:81], v[126:129], v[210:213], v[78:81]
	v_mfma_f32_16x16x32_bf16 v[70:73], v[142:145], v[210:213], v[70:73]
	s_setprio 0
	s_barrier
	s_mov_b32 m0, s48
	v_lshl_add_u64 v[230:231], v[230:231], 0, s[44:45]
	ds_read_b128 v[214:217], v197
	ds_read_b128 v[218:221], v198
	ds_read_b128 v[222:225], v199
	ds_read_b128 v[226:229], v200
	global_load_lds_dwordx4 v[230:231], off
	v_lshl_add_u64 v[230:231], v[232:233], 0, s[44:45]
	s_mov_b32 m0, s49
	s_nop 0
	global_load_lds_dwordx4 v[230:231], off
	s_barrier
	s_waitcnt lgkmcnt(0)
	s_setprio 1
	s_waitcnt lgkmcnt(0)
	v_mfma_f32_16x16x32_bf16 v[130:133], v[214:217], v[146:149], v[130:133]
	v_mfma_f32_16x16x32_bf16 v[114:117], v[222:225], v[146:149], v[114:117]
	v_mfma_f32_16x16x32_bf16 v[106:109], v[214:217], v[154:157], v[106:109]
	v_mfma_f32_16x16x32_bf16 v[98:101], v[222:225], v[154:157], v[98:101]
	v_mfma_f32_16x16x32_bf16 v[90:93], v[214:217], v[176:179], v[90:93]
	v_mfma_f32_16x16x32_bf16 v[82:85], v[222:225], v[176:179], v[82:85]
	v_mfma_f32_16x16x32_bf16 v[74:77], v[214:217], v[206:209], v[74:77]
	v_mfma_f32_16x16x32_bf16 v[66:69], v[222:225], v[206:209], v[66:69]
	v_mfma_f32_16x16x32_bf16 v[130:133], v[218:221], v[150:153], v[130:133]
	v_mfma_f32_16x16x32_bf16 v[114:117], v[226:229], v[150:153], v[114:117]
	v_mfma_f32_16x16x32_bf16 v[106:109], v[218:221], v[158:161], v[106:109]
	v_mfma_f32_16x16x32_bf16 v[98:101], v[226:229], v[158:161], v[98:101]
	v_mfma_f32_16x16x32_bf16 v[90:93], v[218:221], v[202:205], v[90:93]
	v_mfma_f32_16x16x32_bf16 v[82:85], v[226:229], v[202:205], v[82:85]
	v_mfma_f32_16x16x32_bf16 v[74:77], v[218:221], v[210:213], v[74:77]
	v_mfma_f32_16x16x32_bf16 v[66:69], v[226:229], v[210:213], v[66:69]
	s_setprio 0
	s_mov_b32 m0, s50
	v_lshl_add_u64 v[230:231], v[234:235], 0, s[44:45]
	s_barrier
	ds_read_b128 v[146:149], v183 offset:49152
	ds_read_b128 v[150:153], v183 offset:50176
	ds_read_b128 v[154:157], v183 offset:51200
	ds_read_b128 v[158:161], v183 offset:52224
	ds_read_b128 v[176:179], v183 offset:53248
	ds_read_b128 v[202:205], v183 offset:54272
	ds_read_b128 v[206:209], v183 offset:55296
	ds_read_b128 v[210:213], v183 offset:56320
	global_load_lds_dwordx4 v[230:231], off
	v_lshl_add_u64 v[230:231], v[236:237], 0, s[44:45]
	s_mov_b32 m0, s51
	s_nop 0
	global_load_lds_dwordx4 v[230:231], off
	s_barrier
	s_waitcnt lgkmcnt(0)
	s_setprio 1
	s_waitcnt lgkmcnt(0)
	v_mfma_f32_16x16x32_bf16 v[62:65], v[122:125], v[146:149], v[62:65]
	v_mfma_f32_16x16x32_bf16 v[54:57], v[138:141], v[146:149], v[54:57]
	v_mfma_f32_16x16x32_bf16 v[46:49], v[122:125], v[154:157], v[46:49]
	v_mfma_f32_16x16x32_bf16 v[38:41], v[138:141], v[154:157], v[38:41]
	v_mfma_f32_16x16x32_bf16 v[30:33], v[122:125], v[176:179], v[30:33]
	v_mfma_f32_16x16x32_bf16 v[22:25], v[138:141], v[176:179], v[22:25]
	v_mfma_f32_16x16x32_bf16 v[14:17], v[122:125], v[206:209], v[14:17]
	v_mfma_f32_16x16x32_bf16 v[6:9], v[138:141], v[206:209], v[6:9]
	v_mfma_f32_16x16x32_bf16 v[62:65], v[126:129], v[150:153], v[62:65]
	v_mfma_f32_16x16x32_bf16 v[54:57], v[142:145], v[150:153], v[54:57]
	v_mfma_f32_16x16x32_bf16 v[46:49], v[126:129], v[158:161], v[46:49]
	v_mfma_f32_16x16x32_bf16 v[38:41], v[142:145], v[158:161], v[38:41]
	v_mfma_f32_16x16x32_bf16 v[30:33], v[126:129], v[202:205], v[30:33]
	v_mfma_f32_16x16x32_bf16 v[22:25], v[142:145], v[202:205], v[22:25]
	v_mfma_f32_16x16x32_bf16 v[14:17], v[126:129], v[210:213], v[14:17]
	v_mfma_f32_16x16x32_bf16 v[6:9], v[142:145], v[210:213], v[6:9]
	s_setprio 0
	s_barrier
	s_mov_b32 m0, s53
	v_lshl_add_u64 v[122:123], v[238:239], 0, s[44:45]
	global_load_lds_dwordx4 v[122:123], off
	v_lshl_add_u64 v[122:123], v[240:241], 0, s[44:45]
	s_mov_b32 m0, s56
	s_nop 0
	global_load_lds_dwordx4 v[122:123], off
	s_waitcnt vmcnt(6)
	s_barrier
	s_setprio 1
	v_mfma_f32_16x16x32_bf16 v[58:61], v[214:217], v[146:149], v[58:61]
	v_mfma_f32_16x16x32_bf16 v[50:53], v[222:225], v[146:149], v[50:53]
	v_mfma_f32_16x16x32_bf16 v[42:45], v[214:217], v[154:157], v[42:45]
	v_mfma_f32_16x16x32_bf16 v[34:37], v[222:225], v[154:157], v[34:37]
	v_mfma_f32_16x16x32_bf16 v[26:29], v[214:217], v[176:179], v[26:29]
	v_mfma_f32_16x16x32_bf16 v[18:21], v[222:225], v[176:179], v[18:21]
	v_mfma_f32_16x16x32_bf16 v[10:13], v[214:217], v[206:209], v[10:13]
	v_mfma_f32_16x16x32_bf16 v[2:5], v[222:225], v[206:209], v[2:5]
	v_mfma_f32_16x16x32_bf16 v[58:61], v[218:221], v[150:153], v[58:61]
	v_mfma_f32_16x16x32_bf16 v[50:53], v[226:229], v[150:153], v[50:53]
	v_mfma_f32_16x16x32_bf16 v[42:45], v[218:221], v[158:161], v[42:45]
	v_mfma_f32_16x16x32_bf16 v[34:37], v[226:229], v[158:161], v[34:37]
	v_mfma_f32_16x16x32_bf16 v[26:29], v[218:221], v[202:205], v[26:29]
	v_mfma_f32_16x16x32_bf16 v[18:21], v[226:229], v[202:205], v[18:21]
	v_mfma_f32_16x16x32_bf16 v[10:13], v[218:221], v[210:213], v[10:13]
	v_mfma_f32_16x16x32_bf16 v[2:5], v[226:229], v[210:213], v[2:5]
	s_setprio 0
	s_add_u32 s0, s0, 0x100
	s_addc_u32 s1, s1, 0
	s_add_u32 s28, s28, 0x100
	s_addc_u32 s29, s29, 0
	s_cmp_ge_i32 s36, s57
	s_mov_b32 s2, s36
	s_barrier
	s_cbranch_scc0 .LBB0_1104
	s_branch .LBB0_1095

.LBB0_1149:
	ds_read_b128 v[142:145], v176
	ds_read_b128 v[146:149], v177
	ds_read_b128 v[150:153], v178
	ds_read_b128 v[154:157], v179
	s_add_i32 s36, s2, 2
	s_add_u32 s26, s54, 0x80
	s_addc_u32 s3, s55, 0
	s_cmp_eq_u32 s51, s2
	s_cselect_b32 s2, s10, s26
	s_cselect_b32 s3, s11, s3
	s_cselect_b32 s27, s1, s29
	s_cselect_b32 s26, s0, s28
	s_mov_b32 m0, s59
	v_lshl_add_u64 v[168:169], s[54:55], 0, v[134:135]
	ds_read_b128 v[158:161], v174
	ds_read_b128 v[164:167], v174 offset:1024
	ds_read_b128 v[194:197], v174 offset:2048
	ds_read_b128 v[198:201], v174 offset:3072
	ds_read_b128 v[202:205], v174 offset:4096
	ds_read_b128 v[206:209], v174 offset:5120
	ds_read_b128 v[210:213], v174 offset:6144
	ds_read_b128 v[214:217], v174 offset:7168
	global_load_lds_dwordx4 v[168:169], off
	v_lshl_add_u64 v[168:169], s[54:55], 0, v[136:137]
	s_mov_b32 m0, s60
	s_nop 0
	global_load_lds_dwordx4 v[168:169], off
	s_waitcnt lgkmcnt(8)
	s_barrier
	s_waitcnt lgkmcnt(0)
	s_setprio 1
	s_waitcnt lgkmcnt(0)
	v_mfma_f32_16x16x32_bf16 v[126:129], v[142:145], v[158:161], v[126:129]
	v_mfma_f32_16x16x32_bf16 v[122:125], v[150:153], v[158:161], v[122:125]
	v_mfma_f32_16x16x32_bf16 v[110:113], v[142:145], v[194:197], v[110:113]
	v_mfma_f32_16x16x32_bf16 v[106:109], v[150:153], v[194:197], v[106:109]
	v_mfma_f32_16x16x32_bf16 v[94:97], v[142:145], v[202:205], v[94:97]
	v_mfma_f32_16x16x32_bf16 v[90:93], v[150:153], v[202:205], v[90:93]
	v_mfma_f32_16x16x32_bf16 v[78:81], v[142:145], v[210:213], v[78:81]
	v_mfma_f32_16x16x32_bf16 v[74:77], v[150:153], v[210:213], v[74:77]
	v_mfma_f32_16x16x32_bf16 v[126:129], v[146:149], v[164:167], v[126:129]
	v_mfma_f32_16x16x32_bf16 v[122:125], v[154:157], v[164:167], v[122:125]
	v_mfma_f32_16x16x32_bf16 v[110:113], v[146:149], v[198:201], v[110:113]
	v_mfma_f32_16x16x32_bf16 v[106:109], v[154:157], v[198:201], v[106:109]
	v_mfma_f32_16x16x32_bf16 v[94:97], v[146:149], v[206:209], v[94:97]
	v_mfma_f32_16x16x32_bf16 v[90:93], v[154:157], v[206:209], v[90:93]
	v_mfma_f32_16x16x32_bf16 v[78:81], v[146:149], v[214:217], v[78:81]
	v_mfma_f32_16x16x32_bf16 v[74:77], v[154:157], v[214:217], v[74:77]
	s_setprio 0
	s_barrier
	s_mov_b32 m0, s33
	v_lshl_add_u64 v[168:169], s[26:27], 0, v[130:131]
	ds_read_b128 v[218:221], v180
	ds_read_b128 v[222:225], v181
	ds_read_b128 v[226:229], v182
	ds_read_b128 v[230:233], v183
	global_load_lds_dwordx4 v[168:169], off
	v_lshl_add_u64 v[234:235], s[26:27], 0, v[132:133]
	s_mov_b32 m0, s34
	s_nop 0
	global_load_lds_dwordx4 v[234:235], off
	s_barrier
	s_waitcnt lgkmcnt(0)
	s_setprio 1
	s_waitcnt lgkmcnt(0)
	v_mfma_f32_16x16x32_bf16 v[118:121], v[218:221], v[158:161], v[118:121]
	v_mfma_f32_16x16x32_bf16 v[114:117], v[226:229], v[158:161], v[114:117]
	v_mfma_f32_16x16x32_bf16 v[102:105], v[218:221], v[194:197], v[102:105]
	v_mfma_f32_16x16x32_bf16 v[98:101], v[226:229], v[194:197], v[98:101]
	v_mfma_f32_16x16x32_bf16 v[86:89], v[218:221], v[202:205], v[86:89]
	v_mfma_f32_16x16x32_bf16 v[82:85], v[226:229], v[202:205], v[82:85]
	v_mfma_f32_16x16x32_bf16 v[70:73], v[218:221], v[210:213], v[70:73]
	v_mfma_f32_16x16x32_bf16 v[66:69], v[226:229], v[210:213], v[66:69]
	v_mfma_f32_16x16x32_bf16 v[118:121], v[222:225], v[164:167], v[118:121]
	v_mfma_f32_16x16x32_bf16 v[114:117], v[230:233], v[164:167], v[114:117]
	v_mfma_f32_16x16x32_bf16 v[102:105], v[222:225], v[198:201], v[102:105]
	v_mfma_f32_16x16x32_bf16 v[98:101], v[230:233], v[198:201], v[98:101]
	v_mfma_f32_16x16x32_bf16 v[86:89], v[222:225], v[206:209], v[86:89]
	v_mfma_f32_16x16x32_bf16 v[82:85], v[230:233], v[206:209], v[82:85]
	v_mfma_f32_16x16x32_bf16 v[70:73], v[222:225], v[214:217], v[70:73]
	v_mfma_f32_16x16x32_bf16 v[66:69], v[230:233], v[214:217], v[66:69]
	s_setprio 0
	s_mov_b32 m0, s31
	v_lshl_add_u64 v[236:237], s[2:3], 0, v[130:131]
	s_barrier
	ds_read_b128 v[158:161], v174 offset:16384
	ds_read_b128 v[164:167], v174 offset:17408
	ds_read_b128 v[194:197], v174 offset:18432
	ds_read_b128 v[198:201], v174 offset:19456
	ds_read_b128 v[202:205], v174 offset:20480
	ds_read_b128 v[206:209], v174 offset:21504
	ds_read_b128 v[210:213], v174 offset:22528
	ds_read_b128 v[214:217], v174 offset:23552
	global_load_lds_dwordx4 v[236:237], off
	v_lshl_add_u64 v[238:239], s[2:3], 0, v[132:133]
	s_mov_b32 m0, s35
	s_nop 0
	global_load_lds_dwordx4 v[238:239], off
	s_barrier
	s_waitcnt lgkmcnt(0)
	s_setprio 1
	s_waitcnt lgkmcnt(0)
	v_mfma_f32_16x16x32_bf16 v[62:65], v[142:145], v[158:161], v[62:65]
	v_mfma_f32_16x16x32_bf16 v[58:61], v[150:153], v[158:161], v[58:61]
	v_mfma_f32_16x16x32_bf16 v[46:49], v[142:145], v[194:197], v[46:49]
	v_mfma_f32_16x16x32_bf16 v[42:45], v[150:153], v[194:197], v[42:45]
	v_mfma_f32_16x16x32_bf16 v[30:33], v[142:145], v[202:205], v[30:33]
	v_mfma_f32_16x16x32_bf16 v[26:29], v[150:153], v[202:205], v[26:29]
	v_mfma_f32_16x16x32_bf16 v[14:17], v[142:145], v[210:213], v[14:17]
	v_mfma_f32_16x16x32_bf16 v[10:13], v[150:153], v[210:213], v[10:13]
	v_mfma_f32_16x16x32_bf16 v[62:65], v[146:149], v[164:167], v[62:65]
	v_mfma_f32_16x16x32_bf16 v[58:61], v[154:157], v[164:167], v[58:61]
	v_mfma_f32_16x16x32_bf16 v[46:49], v[146:149], v[198:201], v[46:49]
	v_mfma_f32_16x16x32_bf16 v[42:45], v[154:157], v[198:201], v[42:45]
	v_mfma_f32_16x16x32_bf16 v[30:33], v[146:149], v[206:209], v[30:33]
	v_mfma_f32_16x16x32_bf16 v[26:29], v[154:157], v[206:209], v[26:29]
	v_mfma_f32_16x16x32_bf16 v[14:17], v[146:149], v[214:217], v[14:17]
	v_mfma_f32_16x16x32_bf16 v[10:13], v[154:157], v[214:217], v[10:13]
	s_setprio 0
	s_barrier
	s_add_u32 s26, s26, s20
	s_addc_u32 s27, s27, s21
	s_mov_b32 m0, s38
	v_lshl_add_u64 v[240:241], s[26:27], 0, v[130:131]
	global_load_lds_dwordx4 v[240:241], off
	v_lshl_add_u64 v[242:243], s[26:27], 0, v[132:133]
	s_mov_b32 m0, s39
	s_nop 0
	global_load_lds_dwordx4 v[242:243], off
	s_waitcnt vmcnt(6)
	s_barrier
	s_setprio 1
	v_mfma_f32_16x16x32_bf16 v[54:57], v[218:221], v[158:161], v[54:57]
	v_mfma_f32_16x16x32_bf16 v[50:53], v[226:229], v[158:161], v[50:53]
	v_mfma_f32_16x16x32_bf16 v[38:41], v[218:221], v[194:197], v[38:41]
	v_mfma_f32_16x16x32_bf16 v[34:37], v[226:229], v[194:197], v[34:37]
	v_mfma_f32_16x16x32_bf16 v[22:25], v[218:221], v[202:205], v[22:25]
	v_mfma_f32_16x16x32_bf16 v[18:21], v[226:229], v[202:205], v[18:21]
	v_mfma_f32_16x16x32_bf16 v[6:9], v[218:221], v[210:213], v[6:9]
	v_mfma_f32_16x16x32_bf16 v[2:5], v[226:229], v[210:213], v[2:5]
	v_mfma_f32_16x16x32_bf16 v[54:57], v[222:225], v[164:167], v[54:57]
	v_mfma_f32_16x16x32_bf16 v[50:53], v[230:233], v[164:167], v[50:53]
	v_mfma_f32_16x16x32_bf16 v[38:41], v[222:225], v[198:201], v[38:41]
	v_mfma_f32_16x16x32_bf16 v[34:37], v[230:233], v[198:201], v[34:37]
	v_mfma_f32_16x16x32_bf16 v[22:25], v[222:225], v[206:209], v[22:25]
	v_mfma_f32_16x16x32_bf16 v[18:21], v[230:233], v[206:209], v[18:21]
	v_mfma_f32_16x16x32_bf16 v[6:9], v[222:225], v[214:217], v[6:9]
	v_mfma_f32_16x16x32_bf16 v[2:5], v[230:233], v[214:217], v[2:5]
	s_setprio 0
	s_barrier
	ds_read_b128 v[142:145], v184
	ds_read_b128 v[146:149], v185
	ds_read_b128 v[150:153], v186
	ds_read_b128 v[154:157], v187
	s_add_u32 s2, s2, s20
	s_addc_u32 s3, s3, s21
	s_mov_b32 m0, s40
	v_lshl_add_u64 v[218:219], s[2:3], 0, v[130:131]
	ds_read_b128 v[158:161], v174 offset:32768
	ds_read_b128 v[164:167], v174 offset:33792
	ds_read_b128 v[194:197], v174 offset:34816
	ds_read_b128 v[198:201], v174 offset:35840
	ds_read_b128 v[202:205], v174 offset:36864
	ds_read_b128 v[206:209], v174 offset:37888
	ds_read_b128 v[210:213], v174 offset:38912
	ds_read_b128 v[214:217], v174 offset:39936
	global_load_lds_dwordx4 v[218:219], off
	v_lshl_add_u64 v[218:219], s[2:3], 0, v[132:133]
	s_mov_b32 m0, s41
	s_nop 0
	global_load_lds_dwordx4 v[218:219], off
	s_waitcnt lgkmcnt(8)
	s_barrier
	s_waitcnt lgkmcnt(0)
	s_setprio 1
	s_waitcnt lgkmcnt(0)
	v_mfma_f32_16x16x32_bf16 v[126:129], v[142:145], v[158:161], v[126:129]
	v_mfma_f32_16x16x32_bf16 v[122:125], v[150:153], v[158:161], v[122:125]
	v_mfma_f32_16x16x32_bf16 v[110:113], v[142:145], v[194:197], v[110:113]
	v_mfma_f32_16x16x32_bf16 v[106:109], v[150:153], v[194:197], v[106:109]
	v_mfma_f32_16x16x32_bf16 v[94:97], v[142:145], v[202:205], v[94:97]
	v_mfma_f32_16x16x32_bf16 v[90:93], v[150:153], v[202:205], v[90:93]
	v_mfma_f32_16x16x32_bf16 v[78:81], v[142:145], v[210:213], v[78:81]
	v_mfma_f32_16x16x32_bf16 v[74:77], v[150:153], v[210:213], v[74:77]
	v_mfma_f32_16x16x32_bf16 v[126:129], v[146:149], v[164:167], v[126:129]
	v_mfma_f32_16x16x32_bf16 v[122:125], v[154:157], v[164:167], v[122:125]
	v_mfma_f32_16x16x32_bf16 v[110:113], v[146:149], v[198:201], v[110:113]
	v_mfma_f32_16x16x32_bf16 v[106:109], v[154:157], v[198:201], v[106:109]
	v_mfma_f32_16x16x32_bf16 v[94:97], v[146:149], v[206:209], v[94:97]
	v_mfma_f32_16x16x32_bf16 v[90:93], v[154:157], v[206:209], v[90:93]
	v_mfma_f32_16x16x32_bf16 v[78:81], v[146:149], v[214:217], v[78:81]
	v_mfma_f32_16x16x32_bf16 v[74:77], v[154:157], v[214:217], v[74:77]
	s_setprio 0
	s_barrier
	s_mov_b32 m0, s42
	v_lshl_add_u64 v[168:169], v[168:169], 0, s[24:25]
	ds_read_b128 v[218:221], v188
	ds_read_b128 v[222:225], v189
	ds_read_b128 v[226:229], v190
	ds_read_b128 v[230:233], v191
	global_load_lds_dwordx4 v[168:169], off
	v_lshl_add_u64 v[168:169], v[234:235], 0, s[24:25]
	s_mov_b32 m0, s43
	s_nop 0
	global_load_lds_dwordx4 v[168:169], off
	s_barrier
	s_waitcnt lgkmcnt(0)
	s_setprio 1
	s_waitcnt lgkmcnt(0)
	v_mfma_f32_16x16x32_bf16 v[118:121], v[218:221], v[158:161], v[118:121]
	v_mfma_f32_16x16x32_bf16 v[114:117], v[226:229], v[158:161], v[114:117]
	v_mfma_f32_16x16x32_bf16 v[102:105], v[218:221], v[194:197], v[102:105]
	v_mfma_f32_16x16x32_bf16 v[98:101], v[226:229], v[194:197], v[98:101]
	v_mfma_f32_16x16x32_bf16 v[86:89], v[218:221], v[202:205], v[86:89]
	v_mfma_f32_16x16x32_bf16 v[82:85], v[226:229], v[202:205], v[82:85]
	v_mfma_f32_16x16x32_bf16 v[70:73], v[218:221], v[210:213], v[70:73]
	v_mfma_f32_16x16x32_bf16 v[66:69], v[226:229], v[210:213], v[66:69]
	v_mfma_f32_16x16x32_bf16 v[118:121], v[222:225], v[164:167], v[118:121]
	v_mfma_f32_16x16x32_bf16 v[114:117], v[230:233], v[164:167], v[114:117]
	v_mfma_f32_16x16x32_bf16 v[102:105], v[222:225], v[198:201], v[102:105]
	v_mfma_f32_16x16x32_bf16 v[98:101], v[230:233], v[198:201], v[98:101]
	v_mfma_f32_16x16x32_bf16 v[86:89], v[222:225], v[206:209], v[86:89]
	v_mfma_f32_16x16x32_bf16 v[82:85], v[230:233], v[206:209], v[82:85]
	v_mfma_f32_16x16x32_bf16 v[70:73], v[222:225], v[214:217], v[70:73]
	v_mfma_f32_16x16x32_bf16 v[66:69], v[230:233], v[214:217], v[66:69]
	s_setprio 0
	s_mov_b32 m0, s45
	v_lshl_add_u64 v[168:169], v[236:237], 0, s[24:25]
	s_barrier
	ds_read_b128 v[158:161], v174 offset:49152
	ds_read_b128 v[164:167], v174 offset:50176
	ds_read_b128 v[194:197], v174 offset:51200
	ds_read_b128 v[198:201], v174 offset:52224
	ds_read_b128 v[202:205], v174 offset:53248
	ds_read_b128 v[206:209], v174 offset:54272
	ds_read_b128 v[210:213], v174 offset:55296
	ds_read_b128 v[214:217], v174 offset:56320
	global_load_lds_dwordx4 v[168:169], off
	v_lshl_add_u64 v[168:169], v[238:239], 0, s[24:25]
	s_mov_b32 m0, s47
	s_nop 0
	global_load_lds_dwordx4 v[168:169], off
	s_barrier
	s_waitcnt lgkmcnt(0)
	s_setprio 1
	s_waitcnt lgkmcnt(0)
	v_mfma_f32_16x16x32_bf16 v[62:65], v[142:145], v[158:161], v[62:65]
	v_mfma_f32_16x16x32_bf16 v[58:61], v[150:153], v[158:161], v[58:61]
	v_mfma_f32_16x16x32_bf16 v[46:49], v[142:145], v[194:197], v[46:49]
	v_mfma_f32_16x16x32_bf16 v[42:45], v[150:153], v[194:197], v[42:45]
	v_mfma_f32_16x16x32_bf16 v[30:33], v[142:145], v[202:205], v[30:33]
	v_mfma_f32_16x16x32_bf16 v[26:29], v[150:153], v[202:205], v[26:29]
	v_mfma_f32_16x16x32_bf16 v[14:17], v[142:145], v[210:213], v[14:17]
	v_mfma_f32_16x16x32_bf16 v[10:13], v[150:153], v[210:213], v[10:13]
	v_mfma_f32_16x16x32_bf16 v[62:65], v[146:149], v[164:167], v[62:65]
	v_mfma_f32_16x16x32_bf16 v[58:61], v[154:157], v[164:167], v[58:61]
	v_mfma_f32_16x16x32_bf16 v[46:49], v[146:149], v[198:201], v[46:49]
	v_mfma_f32_16x16x32_bf16 v[42:45], v[154:157], v[198:201], v[42:45]
	v_mfma_f32_16x16x32_bf16 v[30:33], v[146:149], v[206:209], v[30:33]
	v_mfma_f32_16x16x32_bf16 v[26:29], v[154:157], v[206:209], v[26:29]
	v_mfma_f32_16x16x32_bf16 v[14:17], v[146:149], v[214:217], v[14:17]
	v_mfma_f32_16x16x32_bf16 v[10:13], v[154:157], v[214:217], v[10:13]
	s_setprio 0
	s_barrier
	s_mov_b32 m0, s48
	v_lshl_add_u64 v[142:143], v[240:241], 0, s[24:25]
	global_load_lds_dwordx4 v[142:143], off
	v_lshl_add_u64 v[142:143], v[242:243], 0, s[24:25]
	s_mov_b32 m0, s49
	s_nop 0
	global_load_lds_dwordx4 v[142:143], off
	s_waitcnt vmcnt(6)
	s_barrier
	s_setprio 1
	v_mfma_f32_16x16x32_bf16 v[54:57], v[218:221], v[158:161], v[54:57]
	v_mfma_f32_16x16x32_bf16 v[50:53], v[226:229], v[158:161], v[50:53]
	v_mfma_f32_16x16x32_bf16 v[38:41], v[218:221], v[194:197], v[38:41]
	v_mfma_f32_16x16x32_bf16 v[34:37], v[226:229], v[194:197], v[34:37]
	v_mfma_f32_16x16x32_bf16 v[22:25], v[218:221], v[202:205], v[22:25]
	v_mfma_f32_16x16x32_bf16 v[18:21], v[226:229], v[202:205], v[18:21]
	v_mfma_f32_16x16x32_bf16 v[6:9], v[218:221], v[210:213], v[6:9]
	v_mfma_f32_16x16x32_bf16 v[2:5], v[226:229], v[210:213], v[2:5]
	v_mfma_f32_16x16x32_bf16 v[54:57], v[222:225], v[164:167], v[54:57]
	v_mfma_f32_16x16x32_bf16 v[50:53], v[230:233], v[164:167], v[50:53]
	v_mfma_f32_16x16x32_bf16 v[38:41], v[222:225], v[198:201], v[38:41]
	v_mfma_f32_16x16x32_bf16 v[34:37], v[230:233], v[198:201], v[34:37]
	v_mfma_f32_16x16x32_bf16 v[22:25], v[222:225], v[206:209], v[22:25]
	v_mfma_f32_16x16x32_bf16 v[18:21], v[230:233], v[206:209], v[18:21]
	v_mfma_f32_16x16x32_bf16 v[6:9], v[222:225], v[214:217], v[6:9]
	v_mfma_f32_16x16x32_bf16 v[2:5], v[230:233], v[214:217], v[2:5]
	s_setprio 0
	s_add_u32 s54, s54, 0x100
	s_addc_u32 s55, s55, 0
	s_add_u32 s28, s28, 0x100
	s_addc_u32 s29, s29, 0
	s_cmp_ge_i32 s36, s50
	s_mov_b32 s2, s36
	s_barrier
	s_cbranch_scc0 .LBB0_1149

.LBB0_1255:
	ds_read_b128 v[146:149], v177
	ds_read_b128 v[150:153], v178
	ds_read_b128 v[154:157], v179
	ds_read_b128 v[158:161], v180
	s_add_i32 s72, s2, 2
	s_add_u32 s28, s26, 0x80
	s_addc_u32 s3, s27, 0
	s_cmp_eq_u32 s64, s2
	s_cselect_b32 s2, s54, s28
	s_cselect_b32 s3, s55, s3
	s_cselect_b32 s29, s1, s53
	s_cselect_b32 s28, s0, s37
	s_mov_b32 m0, s66
	v_lshl_add_u64 v[68:69], s[26:27], 0, v[138:139]
	ds_read_b128 v[164:167], v174
	ds_read_b128 v[168:171], v174 offset:1024
	ds_read_b128 v[194:197], v174 offset:2048
	ds_read_b128 v[198:201], v174 offset:3072
	ds_read_b128 v[206:209], v174 offset:4096
	ds_read_b128 v[210:213], v174 offset:5120
	ds_read_b128 v[214:217], v174 offset:6144
	ds_read_b128 v[218:221], v174 offset:7168
	global_load_lds_dwordx4 v[68:69], off
	v_lshl_add_u64 v[68:69], s[26:27], 0, v[140:141]
	s_mov_b32 m0, s67
	s_nop 0
	global_load_lds_dwordx4 v[68:69], off
	s_waitcnt lgkmcnt(8)
	s_barrier
	s_waitcnt lgkmcnt(0)
	s_setprio 1
	s_waitcnt lgkmcnt(0)
	v_mfma_f32_16x16x32_bf16 v[130:133], v[146:149], v[164:167], v[130:133]
	v_mfma_f32_16x16x32_bf16 v[126:129], v[154:157], v[164:167], v[126:129]
	v_mfma_f32_16x16x32_bf16 v[114:117], v[146:149], v[194:197], v[114:117]
	v_mfma_f32_16x16x32_bf16 v[110:113], v[154:157], v[194:197], v[110:113]
	v_mfma_f32_16x16x32_bf16 v[98:101], v[146:149], v[206:209], v[98:101]
	v_mfma_f32_16x16x32_bf16 v[94:97], v[154:157], v[206:209], v[94:97]
	v_mfma_f32_16x16x32_bf16 v[82:85], v[146:149], v[214:217], v[82:85]
	v_mfma_f32_16x16x32_bf16 v[78:81], v[154:157], v[214:217], v[78:81]
	v_mfma_f32_16x16x32_bf16 v[130:133], v[150:153], v[168:171], v[130:133]
	v_mfma_f32_16x16x32_bf16 v[126:129], v[158:161], v[168:171], v[126:129]
	v_mfma_f32_16x16x32_bf16 v[114:117], v[150:153], v[198:201], v[114:117]
	v_mfma_f32_16x16x32_bf16 v[110:113], v[158:161], v[198:201], v[110:113]
	v_mfma_f32_16x16x32_bf16 v[98:101], v[150:153], v[210:213], v[98:101]
	v_mfma_f32_16x16x32_bf16 v[94:97], v[158:161], v[210:213], v[94:97]
	v_mfma_f32_16x16x32_bf16 v[82:85], v[150:153], v[218:221], v[82:85]
	v_mfma_f32_16x16x32_bf16 v[78:81], v[158:161], v[218:221], v[78:81]
	s_setprio 0
	s_barrier
	s_mov_b32 m0, s38
	v_lshl_add_u64 v[238:239], s[28:29], 0, v[134:135]
	ds_read_b128 v[222:225], v181
	ds_read_b128 v[226:229], v182
	ds_read_b128 v[230:233], v183
	ds_read_b128 v[234:237], v184
	global_load_lds_dwordx4 v[238:239], off
	v_lshl_add_u64 v[240:241], s[28:29], 0, v[136:137]
	s_mov_b32 m0, s39
	s_nop 0
	global_load_lds_dwordx4 v[240:241], off
	s_barrier
	s_waitcnt lgkmcnt(0)
	s_setprio 1
	s_waitcnt lgkmcnt(0)
	v_mfma_f32_16x16x32_bf16 v[122:125], v[222:225], v[164:167], v[122:125]
	v_mfma_f32_16x16x32_bf16 v[118:121], v[230:233], v[164:167], v[118:121]
	v_mfma_f32_16x16x32_bf16 v[106:109], v[222:225], v[194:197], v[106:109]
	v_mfma_f32_16x16x32_bf16 v[102:105], v[230:233], v[194:197], v[102:105]
	v_mfma_f32_16x16x32_bf16 v[90:93], v[222:225], v[206:209], v[90:93]
	v_mfma_f32_16x16x32_bf16 v[86:89], v[230:233], v[206:209], v[86:89]
	v_mfma_f32_16x16x32_bf16 v[74:77], v[222:225], v[214:217], v[74:77]
	v_mfma_f32_16x16x32_bf16 v[68:71], v[230:233], v[214:217], v[70:73]
	v_mfma_f32_16x16x32_bf16 v[122:125], v[226:229], v[168:171], v[122:125]
	v_mfma_f32_16x16x32_bf16 v[118:121], v[234:237], v[168:171], v[118:121]
	v_mfma_f32_16x16x32_bf16 v[106:109], v[226:229], v[198:201], v[106:109]
	v_mfma_f32_16x16x32_bf16 v[102:105], v[234:237], v[198:201], v[102:105]
	v_mfma_f32_16x16x32_bf16 v[90:93], v[226:229], v[210:213], v[90:93]
	v_mfma_f32_16x16x32_bf16 v[86:89], v[234:237], v[210:213], v[86:89]
	v_mfma_f32_16x16x32_bf16 v[74:77], v[226:229], v[218:221], v[74:77]
	v_mfma_f32_16x16x32_bf16 v[68:71], v[234:237], v[218:221], v[68:71]
	s_setprio 0
	s_mov_b32 m0, s35
	v_lshl_add_u64 v[242:243], s[2:3], 0, v[134:135]
	s_barrier
	ds_read_b128 v[164:167], v174 offset:16384
	ds_read_b128 v[168:171], v174 offset:17408
	ds_read_b128 v[194:197], v174 offset:18432
	ds_read_b128 v[198:201], v174 offset:19456
	ds_read_b128 v[206:209], v174 offset:20480
	ds_read_b128 v[210:213], v174 offset:21504
	ds_read_b128 v[214:217], v174 offset:22528
	ds_read_b128 v[218:221], v174 offset:23552
	global_load_lds_dwordx4 v[242:243], off
	v_lshl_add_u64 v[244:245], s[2:3], 0, v[136:137]
	s_mov_b32 m0, s40
	s_nop 0
	global_load_lds_dwordx4 v[244:245], off
	s_barrier
	s_waitcnt lgkmcnt(0)
	s_setprio 1
	s_waitcnt lgkmcnt(0)
	v_mfma_f32_16x16x32_bf16 v[62:65], v[146:149], v[164:167], v[62:65]
	v_mfma_f32_16x16x32_bf16 v[58:61], v[154:157], v[164:167], v[58:61]
	v_mfma_f32_16x16x32_bf16 v[46:49], v[146:149], v[194:197], v[46:49]
	v_mfma_f32_16x16x32_bf16 v[42:45], v[154:157], v[194:197], v[42:45]
	v_mfma_f32_16x16x32_bf16 v[30:33], v[146:149], v[206:209], v[30:33]
	v_mfma_f32_16x16x32_bf16 v[26:29], v[154:157], v[206:209], v[26:29]
	v_mfma_f32_16x16x32_bf16 v[14:17], v[146:149], v[214:217], v[14:17]
	v_mfma_f32_16x16x32_bf16 v[10:13], v[154:157], v[214:217], v[10:13]
	v_mfma_f32_16x16x32_bf16 v[62:65], v[150:153], v[168:171], v[62:65]
	v_mfma_f32_16x16x32_bf16 v[58:61], v[158:161], v[168:171], v[58:61]
	v_mfma_f32_16x16x32_bf16 v[46:49], v[150:153], v[198:201], v[46:49]
	v_mfma_f32_16x16x32_bf16 v[42:45], v[158:161], v[198:201], v[42:45]
	v_mfma_f32_16x16x32_bf16 v[30:33], v[150:153], v[210:213], v[30:33]
	v_mfma_f32_16x16x32_bf16 v[26:29], v[158:161], v[210:213], v[26:29]
	v_mfma_f32_16x16x32_bf16 v[14:17], v[150:153], v[218:221], v[14:17]
	v_mfma_f32_16x16x32_bf16 v[10:13], v[158:161], v[218:221], v[10:13]
	s_setprio 0
	s_barrier
	s_add_u32 s28, s28, s20
	s_addc_u32 s29, s29, s21
	s_mov_b32 m0, s41
	v_lshl_add_u64 v[246:247], s[28:29], 0, v[134:135]
	global_load_lds_dwordx4 v[246:247], off
	v_lshl_add_u64 v[248:249], s[28:29], 0, v[136:137]
	s_mov_b32 m0, s42
	s_nop 0
	global_load_lds_dwordx4 v[248:249], off
	s_waitcnt vmcnt(6)
	s_barrier
	s_setprio 1
	v_mfma_f32_16x16x32_bf16 v[54:57], v[222:225], v[164:167], v[54:57]
	v_mfma_f32_16x16x32_bf16 v[50:53], v[230:233], v[164:167], v[50:53]
	v_mfma_f32_16x16x32_bf16 v[38:41], v[222:225], v[194:197], v[38:41]
	v_mfma_f32_16x16x32_bf16 v[34:37], v[230:233], v[194:197], v[34:37]
	v_mfma_f32_16x16x32_bf16 v[22:25], v[222:225], v[206:209], v[22:25]
	v_mfma_f32_16x16x32_bf16 v[18:21], v[230:233], v[206:209], v[18:21]
	v_mfma_f32_16x16x32_bf16 v[6:9], v[222:225], v[214:217], v[6:9]
	v_mfma_f32_16x16x32_bf16 v[2:5], v[230:233], v[214:217], v[2:5]
	v_mfma_f32_16x16x32_bf16 v[54:57], v[226:229], v[168:171], v[54:57]
	v_mfma_f32_16x16x32_bf16 v[50:53], v[234:237], v[168:171], v[50:53]
	v_mfma_f32_16x16x32_bf16 v[38:41], v[226:229], v[198:201], v[38:41]
	v_mfma_f32_16x16x32_bf16 v[34:37], v[234:237], v[198:201], v[34:37]
	v_mfma_f32_16x16x32_bf16 v[22:25], v[226:229], v[210:213], v[22:25]
	v_mfma_f32_16x16x32_bf16 v[18:21], v[234:237], v[210:213], v[18:21]
	v_mfma_f32_16x16x32_bf16 v[6:9], v[226:229], v[218:221], v[6:9]
	v_mfma_f32_16x16x32_bf16 v[2:5], v[234:237], v[218:221], v[2:5]
	s_setprio 0
	s_barrier
	ds_read_b128 v[146:149], v185
	ds_read_b128 v[150:153], v186
	ds_read_b128 v[154:157], v187
	ds_read_b128 v[158:161], v188
	s_add_u32 s2, s2, s20
	s_addc_u32 s3, s3, s21
	s_mov_b32 m0, s43
	v_lshl_add_u64 v[72:73], s[2:3], 0, v[134:135]
	ds_read_b128 v[164:167], v174 offset:32768
	ds_read_b128 v[168:171], v174 offset:33792
	ds_read_b128 v[194:197], v174 offset:34816
	ds_read_b128 v[198:201], v174 offset:35840
	ds_read_b128 v[206:209], v174 offset:36864
	ds_read_b128 v[210:213], v174 offset:37888
	ds_read_b128 v[214:217], v174 offset:38912
	ds_read_b128 v[218:221], v174 offset:39936
	global_load_lds_dwordx4 v[72:73], off
	v_lshl_add_u64 v[72:73], s[2:3], 0, v[136:137]
	s_mov_b32 m0, s45
	s_nop 0
	global_load_lds_dwordx4 v[72:73], off
	s_waitcnt lgkmcnt(8)
	s_barrier
	s_waitcnt lgkmcnt(0)
	s_setprio 1
	s_waitcnt lgkmcnt(0)
	v_mfma_f32_16x16x32_bf16 v[130:133], v[146:149], v[164:167], v[130:133]
	v_mfma_f32_16x16x32_bf16 v[126:129], v[154:157], v[164:167], v[126:129]
	v_mfma_f32_16x16x32_bf16 v[114:117], v[146:149], v[194:197], v[114:117]
	v_mfma_f32_16x16x32_bf16 v[110:113], v[154:157], v[194:197], v[110:113]
	v_mfma_f32_16x16x32_bf16 v[98:101], v[146:149], v[206:209], v[98:101]
	v_mfma_f32_16x16x32_bf16 v[94:97], v[154:157], v[206:209], v[94:97]
	v_mfma_f32_16x16x32_bf16 v[82:85], v[146:149], v[214:217], v[82:85]
	v_mfma_f32_16x16x32_bf16 v[78:81], v[154:157], v[214:217], v[78:81]
	v_mfma_f32_16x16x32_bf16 v[130:133], v[150:153], v[168:171], v[130:133]
	v_mfma_f32_16x16x32_bf16 v[126:129], v[158:161], v[168:171], v[126:129]
	v_mfma_f32_16x16x32_bf16 v[114:117], v[150:153], v[198:201], v[114:117]
	v_mfma_f32_16x16x32_bf16 v[110:113], v[158:161], v[198:201], v[110:113]
	v_mfma_f32_16x16x32_bf16 v[98:101], v[150:153], v[210:213], v[98:101]
	v_mfma_f32_16x16x32_bf16 v[94:97], v[158:161], v[210:213], v[94:97]
	v_mfma_f32_16x16x32_bf16 v[82:85], v[150:153], v[218:221], v[82:85]
	v_mfma_f32_16x16x32_bf16 v[78:81], v[158:161], v[218:221], v[78:81]
	s_setprio 0
	s_barrier
	s_mov_b32 m0, s50
	v_lshl_add_u64 v[72:73], v[238:239], 0, s[24:25]
	ds_read_b128 v[222:225], v189
	ds_read_b128 v[226:229], v190
	ds_read_b128 v[230:233], v191
	ds_read_b128 v[234:237], v192
	global_load_lds_dwordx4 v[72:73], off
	v_lshl_add_u64 v[72:73], v[240:241], 0, s[24:25]
	s_mov_b32 m0, s51
	s_nop 0
	global_load_lds_dwordx4 v[72:73], off
	s_barrier
	s_waitcnt lgkmcnt(0)
	s_setprio 1
	s_waitcnt lgkmcnt(0)
	v_mfma_f32_16x16x32_bf16 v[122:125], v[222:225], v[164:167], v[122:125]
	v_mfma_f32_16x16x32_bf16 v[118:121], v[230:233], v[164:167], v[118:121]
	v_mfma_f32_16x16x32_bf16 v[106:109], v[222:225], v[194:197], v[106:109]
	v_mfma_f32_16x16x32_bf16 v[102:105], v[230:233], v[194:197], v[102:105]
	v_mfma_f32_16x16x32_bf16 v[90:93], v[222:225], v[206:209], v[90:93]
	v_mfma_f32_16x16x32_bf16 v[86:89], v[230:233], v[206:209], v[86:89]
	v_mfma_f32_16x16x32_bf16 v[72:75], v[222:225], v[214:217], v[74:77]
	v_mfma_f32_16x16x32_bf16 v[68:71], v[230:233], v[214:217], v[68:71]
	v_mfma_f32_16x16x32_bf16 v[122:125], v[226:229], v[168:171], v[122:125]
	v_mfma_f32_16x16x32_bf16 v[118:121], v[234:237], v[168:171], v[118:121]
	v_mfma_f32_16x16x32_bf16 v[106:109], v[226:229], v[198:201], v[106:109]
	v_mfma_f32_16x16x32_bf16 v[102:105], v[234:237], v[198:201], v[102:105]
	v_mfma_f32_16x16x32_bf16 v[90:93], v[226:229], v[210:213], v[90:93]
	v_mfma_f32_16x16x32_bf16 v[86:89], v[234:237], v[210:213], v[86:89]
	v_mfma_f32_16x16x32_bf16 v[74:77], v[226:229], v[218:221], v[72:75]
	v_mfma_f32_16x16x32_bf16 v[70:73], v[234:237], v[218:221], v[68:71]
	s_setprio 0
	s_mov_b32 m0, s60
	s_nop 0
	v_lshl_add_u64 v[68:69], v[242:243], 0, s[24:25]
	s_barrier
	ds_read_b128 v[164:167], v174 offset:49152
	ds_read_b128 v[168:171], v174 offset:50176
	ds_read_b128 v[194:197], v174 offset:51200
	ds_read_b128 v[198:201], v174 offset:52224
	ds_read_b128 v[206:209], v174 offset:53248
	ds_read_b128 v[210:213], v174 offset:54272
	ds_read_b128 v[214:217], v174 offset:55296
	ds_read_b128 v[218:221], v174 offset:56320
	global_load_lds_dwordx4 v[68:69], off
	v_lshl_add_u64 v[68:69], v[244:245], 0, s[24:25]
	s_mov_b32 m0, s61
	s_nop 0
	global_load_lds_dwordx4 v[68:69], off
	s_barrier
	s_waitcnt lgkmcnt(0)
	s_setprio 1
	s_waitcnt lgkmcnt(0)
	v_mfma_f32_16x16x32_bf16 v[62:65], v[146:149], v[164:167], v[62:65]
	v_mfma_f32_16x16x32_bf16 v[58:61], v[154:157], v[164:167], v[58:61]
	v_mfma_f32_16x16x32_bf16 v[46:49], v[146:149], v[194:197], v[46:49]
	v_mfma_f32_16x16x32_bf16 v[42:45], v[154:157], v[194:197], v[42:45]
	v_mfma_f32_16x16x32_bf16 v[30:33], v[146:149], v[206:209], v[30:33]
	v_mfma_f32_16x16x32_bf16 v[26:29], v[154:157], v[206:209], v[26:29]
	v_mfma_f32_16x16x32_bf16 v[14:17], v[146:149], v[214:217], v[14:17]
	v_mfma_f32_16x16x32_bf16 v[10:13], v[154:157], v[214:217], v[10:13]
	v_mfma_f32_16x16x32_bf16 v[62:65], v[150:153], v[168:171], v[62:65]
	v_mfma_f32_16x16x32_bf16 v[58:61], v[158:161], v[168:171], v[58:61]
	v_mfma_f32_16x16x32_bf16 v[46:49], v[150:153], v[198:201], v[46:49]
	v_mfma_f32_16x16x32_bf16 v[42:45], v[158:161], v[198:201], v[42:45]
	v_mfma_f32_16x16x32_bf16 v[30:33], v[150:153], v[210:213], v[30:33]
	v_mfma_f32_16x16x32_bf16 v[26:29], v[158:161], v[210:213], v[26:29]
	v_mfma_f32_16x16x32_bf16 v[14:17], v[150:153], v[218:221], v[14:17]
	v_mfma_f32_16x16x32_bf16 v[10:13], v[158:161], v[218:221], v[10:13]
	s_setprio 0
	s_barrier
	s_mov_b32 m0, s62
	v_lshl_add_u64 v[68:69], v[246:247], 0, s[24:25]
	global_load_lds_dwordx4 v[68:69], off
	v_lshl_add_u64 v[68:69], v[248:249], 0, s[24:25]
	s_mov_b32 m0, s63
	s_nop 0
	global_load_lds_dwordx4 v[68:69], off
	s_waitcnt vmcnt(6)
	s_barrier
	s_setprio 1
	v_mfma_f32_16x16x32_bf16 v[54:57], v[222:225], v[164:167], v[54:57]
	v_mfma_f32_16x16x32_bf16 v[50:53], v[230:233], v[164:167], v[50:53]
	v_mfma_f32_16x16x32_bf16 v[38:41], v[222:225], v[194:197], v[38:41]
	v_mfma_f32_16x16x32_bf16 v[34:37], v[230:233], v[194:197], v[34:37]
	v_mfma_f32_16x16x32_bf16 v[22:25], v[222:225], v[206:209], v[22:25]
	v_mfma_f32_16x16x32_bf16 v[18:21], v[230:233], v[206:209], v[18:21]
	v_mfma_f32_16x16x32_bf16 v[6:9], v[222:225], v[214:217], v[6:9]
	v_mfma_f32_16x16x32_bf16 v[2:5], v[230:233], v[214:217], v[2:5]
	v_mfma_f32_16x16x32_bf16 v[54:57], v[226:229], v[168:171], v[54:57]
	v_mfma_f32_16x16x32_bf16 v[50:53], v[234:237], v[168:171], v[50:53]
	v_mfma_f32_16x16x32_bf16 v[38:41], v[226:229], v[198:201], v[38:41]
	v_mfma_f32_16x16x32_bf16 v[34:37], v[234:237], v[198:201], v[34:37]
	v_mfma_f32_16x16x32_bf16 v[22:25], v[226:229], v[210:213], v[22:25]
	v_mfma_f32_16x16x32_bf16 v[18:21], v[234:237], v[210:213], v[18:21]
	v_mfma_f32_16x16x32_bf16 v[6:9], v[226:229], v[218:221], v[6:9]
	v_mfma_f32_16x16x32_bf16 v[2:5], v[234:237], v[218:221], v[2:5]
	s_setprio 0
	s_add_u32 s26, s26, 0x100
	s_addc_u32 s27, s27, 0
	s_add_u32 s37, s37, 0x100
	s_addc_u32 s53, s53, 0
	s_cmp_ge_i32 s72, s49
	s_mov_b32 s2, s72
	s_barrier
	s_cbranch_scc0 .LBB0_1255

	.amdhsa_kernel _Z14fwd_megakernel6Params
		.amdhsa_group_segment_fixed_size 131088
		.amdhsa_private_segment_fixed_size 0
		.amdhsa_kernarg_size 408
		.amdhsa_user_sgpr_count 2
		.amdhsa_user_sgpr_dispatch_ptr 0
		.amdhsa_user_sgpr_queue_ptr 0
		.amdhsa_user_sgpr_kernarg_segment_ptr 1
		.amdhsa_user_sgpr_dispatch_id 0
		.amdhsa_user_sgpr_kernarg_preload_length 0
		.amdhsa_user_sgpr_kernarg_preload_offset 0
		.amdhsa_user_sgpr_private_segment_size 0
		.amdhsa_uses_dynamic_stack 0
		.amdhsa_enable_private_segment 0
		.amdhsa_system_sgpr_workgroup_id_x 1
		.amdhsa_system_sgpr_workgroup_id_y 0
		.amdhsa_system_sgpr_workgroup_id_z 0
		.amdhsa_system_sgpr_workgroup_info 0
		.amdhsa_system_vgpr_workitem_id 2
		.amdhsa_next_free_vgpr 252
		.amdhsa_next_free_sgpr 102
		.amdhsa_accum_offset 252
		.amdhsa_reserve_vcc 1
		.amdhsa_float_round_mode_32 0
		.amdhsa_float_round_mode_16_64 0
		.amdhsa_float_denorm_mode_32 3
		.amdhsa_float_denorm_mode_16_64 3
		.amdhsa_dx10_clamp 1
		.amdhsa_ieee_mode 1
		.amdhsa_fp16_overflow 0
		.amdhsa_tg_split 0
		.amdhsa_exception_fp_ieee_invalid_op 0
		.amdhsa_exception_fp_denorm_src 0
		.amdhsa_exception_fp_ieee_div_zero 0
		.amdhsa_exception_fp_ieee_overflow 0
		.amdhsa_exception_fp_ieee_underflow 0
		.amdhsa_exception_fp_ieee_inexact 0
		.amdhsa_exception_int_div_zero 0
	.end_amdhsa_kernel

amdhsa.kernels:
  - .agpr_count:     0
    .args:
      - .offset:         0
        .size:           152
        .value_kind:     by_value
      - .offset:         152
        .size:           4
        .value_kind:     hidden_block_count_x
      - .offset:         156
        .size:           4
        .value_kind:     hidden_block_count_y
      - .offset:         160
        .size:           4
        .value_kind:     hidden_block_count_z
      - .offset:         164
        .size:           2
        .value_kind:     hidden_group_size_x
      - .offset:         166
        .size:           2
        .value_kind:     hidden_group_size_y
      - .offset:         168
        .size:           2
        .value_kind:     hidden_group_size_z
      - .offset:         170
        .size:           2
        .value_kind:     hidden_remainder_x
      - .offset:         172
        .size:           2
        .value_kind:     hidden_remainder_y
      - .offset:         174
        .size:           2
        .value_kind:     hidden_remainder_z
      - .offset:         192
        .size:           8
        .value_kind:     hidden_global_offset_x
      - .offset:         200
        .size:           8
        .value_kind:     hidden_global_offset_y
      - .offset:         208
        .size:           8
        .value_kind:     hidden_global_offset_z
      - .offset:         216
        .size:           2
        .value_kind:     hidden_grid_dims
      - .offset:         240
        .size:           8
        .value_kind:     hidden_multigrid_sync_arg
    .group_segment_fixed_size: 131088
    .kernarg_segment_align: 8
    .kernarg_segment_size: 408
    .language:       OpenCL C
    .language_version:
      - 2
      - 0
    .max_flat_workgroup_size: 512
    .name:           _Z14fwd_megakernel6Params
    .private_segment_fixed_size: 0
    .sgpr_count:     108
    .sgpr_spill_count: 79
    .symbol:         _Z14fwd_megakernel6Params.kd
    .uniform_work_group_size: 1
    .uses_dynamic_stack: false
    .vgpr_count:     252
    .vgpr_spill_count: 0
    .wavefront_size: 64
